# s29 + setprio_none: all s_setprio flips around the K-loop MFMA blocks removed
# baseline (speedup 1.0000x reference)
.LBB0_124:
	ds_read_b128 v[160:163], v202
	ds_read_b128 v[164:167], v202 offset:1024
	ds_read_b128 v[168:171], v202 offset:2048
	ds_read_b128 v[172:175], v202 offset:3072
	ds_read_b128 v[208:211], v203
	ds_read_b128 v[212:215], v203 offset:1024
	ds_read_b128 v[218:221], v203 offset:2048
	ds_read_b128 v[222:225], v203 offset:3072
	s_add_i32 s15, s14, 2
	s_add_u32 s10, s12, s6
	s_addc_u32 s11, s13, s7
	s_cmpk_eq_i32 s6, 0x700
	s_cselect_b32 s16, s85, s9
	s_cselect_b32 s17, s84, s8
	s_cselect_b32 s86, 0, s15
	s_cselect_b32 s11, s57, s11
	s_cselect_b32 s10, s56, s10
	v_lshl_add_u64 v[192:193], v[156:157], 0, s[6:7]
	s_add_i32 m0, s39, 0xc000
	ds_read_b128 v[226:229], v204
	ds_read_b128 v[230:233], v204 offset:1024
	ds_read_b128 v[234:237], v204 offset:2048
	ds_read_b128 v[238:241], v204 offset:3072
	ds_read_b128 v[242:245], v204 offset:4096
	ds_read_b128 v[246:249], v204 offset:5120
	ds_read_b128 v[250:253], v204 offset:6144
	ds_read_b128 v[186:189], v204 offset:7168
	global_load_lds_dwordx4 v[192:193], off
	v_lshl_add_u64 v[192:193], v[158:159], 0, s[6:7]
	s_add_i32 m0, s39, 0xe000
	s_nop 0
	global_load_lds_dwordx4 v[192:193], off
	s_waitcnt vmcnt(8)
	s_waitcnt lgkmcnt(0)
	s_barrier
	v_mfma_f32_16x16x32_bf16 v[124:127], v[160:163], v[226:229], v[124:127]
	v_mfma_f32_16x16x32_bf16 v[120:123], v[168:171], v[226:229], v[120:123]
	v_mfma_f32_16x16x32_bf16 v[108:111], v[160:163], v[234:237], v[108:111]
	v_mfma_f32_16x16x32_bf16 v[104:107], v[168:171], v[234:237], v[104:107]
	v_mfma_f32_16x16x32_bf16 v[92:95], v[160:163], v[242:245], v[92:95]
	v_mfma_f32_16x16x32_bf16 v[88:91], v[168:171], v[242:245], v[88:91]
	v_mfma_f32_16x16x32_bf16 v[76:79], v[160:163], v[250:253], v[76:79]
	v_mfma_f32_16x16x32_bf16 v[72:75], v[168:171], v[250:253], v[72:75]
	v_mfma_f32_16x16x32_bf16 v[124:127], v[164:167], v[230:233], v[124:127]
	v_mfma_f32_16x16x32_bf16 v[120:123], v[172:175], v[230:233], v[120:123]
	v_mfma_f32_16x16x32_bf16 v[108:111], v[164:167], v[238:241], v[108:111]
	v_mfma_f32_16x16x32_bf16 v[104:107], v[172:175], v[238:241], v[104:107]
	v_mfma_f32_16x16x32_bf16 v[92:95], v[164:167], v[246:249], v[92:95]
	v_mfma_f32_16x16x32_bf16 v[88:91], v[172:175], v[246:249], v[88:91]
	v_mfma_f32_16x16x32_bf16 v[76:79], v[164:167], v[186:189], v[76:79]
	v_mfma_f32_16x16x32_bf16 v[72:75], v[172:175], v[186:189], v[72:75]
	v_mfma_f32_16x16x32_bf16 v[116:119], v[208:211], v[226:229], v[116:119]
	v_mfma_f32_16x16x32_bf16 v[112:115], v[218:221], v[226:229], v[112:115]
	v_mfma_f32_16x16x32_bf16 v[100:103], v[208:211], v[234:237], v[100:103]
	v_mfma_f32_16x16x32_bf16 v[96:99], v[218:221], v[234:237], v[96:99]
	v_mfma_f32_16x16x32_bf16 v[84:87], v[208:211], v[242:245], v[84:87]
	v_mfma_f32_16x16x32_bf16 v[80:83], v[218:221], v[242:245], v[80:83]
	v_mfma_f32_16x16x32_bf16 v[68:71], v[208:211], v[250:253], v[68:71]
	v_mfma_f32_16x16x32_bf16 v[64:67], v[218:221], v[250:253], v[64:67]
	v_mfma_f32_16x16x32_bf16 v[116:119], v[212:215], v[230:233], v[116:119]
	v_mfma_f32_16x16x32_bf16 v[112:115], v[222:225], v[230:233], v[112:115]
	v_mfma_f32_16x16x32_bf16 v[100:103], v[212:215], v[238:241], v[100:103]
	v_mfma_f32_16x16x32_bf16 v[96:99], v[222:225], v[238:241], v[96:99]
	v_mfma_f32_16x16x32_bf16 v[84:87], v[212:215], v[246:249], v[84:87]
	v_mfma_f32_16x16x32_bf16 v[80:83], v[222:225], v[246:249], v[80:83]
	v_mfma_f32_16x16x32_bf16 v[68:71], v[212:215], v[186:189], v[68:71]
	v_mfma_f32_16x16x32_bf16 v[64:67], v[222:225], v[186:189], v[64:67]
	s_barrier
	s_add_i32 s18, s94, s97
	v_lshl_add_u64 v[192:193], s[10:11], 0, v[132:133]
	s_mov_b32 m0, s18
	ds_read_b128 v[186:189], v204 offset:16384
	ds_read_b128 v[226:229], v204 offset:17408
	ds_read_b128 v[230:233], v204 offset:18432
	ds_read_b128 v[234:237], v204 offset:19456
	ds_read_b128 v[238:241], v204 offset:20480
	ds_read_b128 v[242:245], v204 offset:21504
	ds_read_b128 v[246:249], v204 offset:22528
	ds_read_b128 v[250:253], v204 offset:23552
	global_load_lds_dwordx4 v[192:193], off
	s_add_i32 m0, s18, 0x2000
	s_add_u32 s18, s10, 0x40000
	v_lshl_add_u64 v[196:197], s[10:11], 0, v[136:137]
	s_addc_u32 s19, s11, 0
	s_add_i32 s20, s95, s97
	global_load_lds_dwordx4 v[196:197], off
	s_mov_b32 m0, s20
	s_nop 0
	global_load_lds_dwordx4 v132, s[18:19]
	v_lshl_add_u64 v[176:177], s[18:19], 0, v[136:137]
	s_add_i32 m0, s20, 0x2000
	s_lshl_b64 s[18:19], s[86:87], 7
	s_add_u32 s18, s17, s18
	s_addc_u32 s19, s16, s19
	global_load_lds_dwordx4 v[176:177], off
	s_mov_b32 m0, s39
	s_nop 0
	global_load_lds_dwordx4 v130, s[18:19]
	s_mov_b32 m0, s91
	s_nop 0
	global_load_lds_dwordx4 v134, s[18:19]
	s_waitcnt vmcnt(8)
	s_waitcnt lgkmcnt(0)
	s_barrier
	v_mfma_f32_16x16x32_bf16 v[60:63], v[160:163], v[186:189], v[60:63]
	v_mfma_f32_16x16x32_bf16 v[56:59], v[168:171], v[186:189], v[56:59]
	v_mfma_f32_16x16x32_bf16 v[44:47], v[160:163], v[230:233], v[44:47]
	v_mfma_f32_16x16x32_bf16 v[40:43], v[168:171], v[230:233], v[40:43]
	v_mfma_f32_16x16x32_bf16 v[28:31], v[160:163], v[238:241], v[28:31]
	v_mfma_f32_16x16x32_bf16 v[24:27], v[168:171], v[238:241], v[24:27]
	v_mfma_f32_16x16x32_bf16 v[12:15], v[160:163], v[246:249], v[12:15]
	v_mfma_f32_16x16x32_bf16 v[8:11], v[168:171], v[246:249], v[8:11]
	v_mfma_f32_16x16x32_bf16 v[60:63], v[164:167], v[226:229], v[60:63]
	v_mfma_f32_16x16x32_bf16 v[56:59], v[172:175], v[226:229], v[56:59]
	v_mfma_f32_16x16x32_bf16 v[44:47], v[164:167], v[234:237], v[44:47]
	v_mfma_f32_16x16x32_bf16 v[40:43], v[172:175], v[234:237], v[40:43]
	v_mfma_f32_16x16x32_bf16 v[28:31], v[164:167], v[242:245], v[28:31]
	v_mfma_f32_16x16x32_bf16 v[24:27], v[172:175], v[242:245], v[24:27]
	v_mfma_f32_16x16x32_bf16 v[12:15], v[164:167], v[250:253], v[12:15]
	v_mfma_f32_16x16x32_bf16 v[8:11], v[172:175], v[250:253], v[8:11]
	v_mfma_f32_16x16x32_bf16 v[52:55], v[208:211], v[186:189], v[52:55]
	v_mfma_f32_16x16x32_bf16 v[48:51], v[218:221], v[186:189], v[48:51]
	v_mfma_f32_16x16x32_bf16 v[36:39], v[208:211], v[230:233], v[36:39]
	v_mfma_f32_16x16x32_bf16 v[32:35], v[218:221], v[230:233], v[32:35]
	v_mfma_f32_16x16x32_bf16 v[20:23], v[208:211], v[238:241], v[20:23]
	v_mfma_f32_16x16x32_bf16 v[16:19], v[218:221], v[238:241], v[16:19]
	v_mfma_f32_16x16x32_bf16 v[4:7], v[208:211], v[246:249], v[4:7]
	v_mfma_f32_16x16x32_bf16 v[0:3], v[218:221], v[246:249], v[0:3]
	v_mfma_f32_16x16x32_bf16 v[52:55], v[212:215], v[226:229], v[52:55]
	v_mfma_f32_16x16x32_bf16 v[48:51], v[222:225], v[226:229], v[48:51]
	v_mfma_f32_16x16x32_bf16 v[36:39], v[212:215], v[234:237], v[36:39]
	v_mfma_f32_16x16x32_bf16 v[32:35], v[222:225], v[234:237], v[32:35]
	v_mfma_f32_16x16x32_bf16 v[20:23], v[212:215], v[242:245], v[20:23]
	v_mfma_f32_16x16x32_bf16 v[16:19], v[222:225], v[242:245], v[16:19]
	v_mfma_f32_16x16x32_bf16 v[4:7], v[212:215], v[250:253], v[4:7]
	v_mfma_f32_16x16x32_bf16 v[0:3], v[222:225], v[250:253], v[0:3]
	s_barrier
	s_add_i32 s20, 0, 0x18000
	v_add_u32_e32 v138, s20, v179
	s_add_i32 s21, 0, 0x1c000
	ds_read_b128 v[160:163], v138
	ds_read_b128 v[164:167], v138 offset:1024
	ds_read_b128 v[168:171], v138 offset:2048
	ds_read_b128 v[172:175], v138 offset:3072
	v_add_u32_e32 v138, s21, v179
	ds_read_b128 v[186:189], v138
	ds_read_b128 v[208:211], v138 offset:1024
	ds_read_b128 v[212:215], v138 offset:2048
	ds_read_b128 v[218:221], v138 offset:3072
	s_add_u32 s18, s18, 0x40000
	s_addc_u32 s19, s19, 0
	s_mov_b32 m0, s33
	ds_read_b128 v[222:225], v204 offset:32768
	ds_read_b128 v[226:229], v204 offset:33792
	ds_read_b128 v[230:233], v204 offset:34816
	ds_read_b128 v[234:237], v204 offset:35840
	ds_read_b128 v[238:241], v204 offset:36864
	ds_read_b128 v[242:245], v204 offset:37888
	ds_read_b128 v[246:249], v204 offset:38912
	ds_read_b128 v[250:253], v204 offset:39936
	global_load_lds_dwordx4 v130, s[18:19]
	s_mov_b32 m0, s58
	s_nop 0
	global_load_lds_dwordx4 v134, s[18:19]
	s_waitcnt vmcnt(8)
	s_waitcnt lgkmcnt(0)
	s_barrier
	v_mfma_f32_16x16x32_bf16 v[124:127], v[160:163], v[222:225], v[124:127]
	v_mfma_f32_16x16x32_bf16 v[120:123], v[168:171], v[222:225], v[120:123]
	v_mfma_f32_16x16x32_bf16 v[108:111], v[160:163], v[230:233], v[108:111]
	v_mfma_f32_16x16x32_bf16 v[104:107], v[168:171], v[230:233], v[104:107]
	v_mfma_f32_16x16x32_bf16 v[92:95], v[160:163], v[238:241], v[92:95]
	v_mfma_f32_16x16x32_bf16 v[88:91], v[168:171], v[238:241], v[88:91]
	v_mfma_f32_16x16x32_bf16 v[76:79], v[160:163], v[246:249], v[76:79]
	v_mfma_f32_16x16x32_bf16 v[72:75], v[168:171], v[246:249], v[72:75]
	v_mfma_f32_16x16x32_bf16 v[124:127], v[164:167], v[226:229], v[124:127]
	v_mfma_f32_16x16x32_bf16 v[120:123], v[172:175], v[226:229], v[120:123]
	v_mfma_f32_16x16x32_bf16 v[108:111], v[164:167], v[234:237], v[108:111]
	v_mfma_f32_16x16x32_bf16 v[104:107], v[172:175], v[234:237], v[104:107]
	v_mfma_f32_16x16x32_bf16 v[92:95], v[164:167], v[242:245], v[92:95]
	v_mfma_f32_16x16x32_bf16 v[88:91], v[172:175], v[242:245], v[88:91]
	v_mfma_f32_16x16x32_bf16 v[76:79], v[164:167], v[250:253], v[76:79]
	v_mfma_f32_16x16x32_bf16 v[72:75], v[172:175], v[250:253], v[72:75]
	v_mfma_f32_16x16x32_bf16 v[116:119], v[186:189], v[222:225], v[116:119]
	v_mfma_f32_16x16x32_bf16 v[112:115], v[212:215], v[222:225], v[112:115]
	v_mfma_f32_16x16x32_bf16 v[100:103], v[186:189], v[230:233], v[100:103]
	v_mfma_f32_16x16x32_bf16 v[96:99], v[212:215], v[230:233], v[96:99]
	v_mfma_f32_16x16x32_bf16 v[84:87], v[186:189], v[238:241], v[84:87]
	v_mfma_f32_16x16x32_bf16 v[80:83], v[212:215], v[238:241], v[80:83]
	v_mfma_f32_16x16x32_bf16 v[68:71], v[186:189], v[246:249], v[68:71]
	v_mfma_f32_16x16x32_bf16 v[64:67], v[212:215], v[246:249], v[64:67]
	v_mfma_f32_16x16x32_bf16 v[116:119], v[208:211], v[226:229], v[116:119]
	v_mfma_f32_16x16x32_bf16 v[112:115], v[218:221], v[226:229], v[112:115]
	v_mfma_f32_16x16x32_bf16 v[100:103], v[208:211], v[234:237], v[100:103]
	v_mfma_f32_16x16x32_bf16 v[96:99], v[218:221], v[234:237], v[96:99]
	v_mfma_f32_16x16x32_bf16 v[84:87], v[208:211], v[242:245], v[84:87]
	v_mfma_f32_16x16x32_bf16 v[80:83], v[218:221], v[242:245], v[80:83]
	v_mfma_f32_16x16x32_bf16 v[68:71], v[208:211], v[250:253], v[68:71]
	v_mfma_f32_16x16x32_bf16 v[64:67], v[218:221], v[250:253], v[64:67]
	s_barrier
	s_add_i32 s18, s20, s97
	v_lshl_add_u64 v[176:177], v[192:193], 0, s[64:65]
	s_mov_b32 m0, s18
	ds_read_b128 v[222:225], v204 offset:49152
	ds_read_b128 v[226:229], v204 offset:50176
	ds_read_b128 v[230:233], v204 offset:51200
	ds_read_b128 v[234:237], v204 offset:52224
	ds_read_b128 v[238:241], v204 offset:53248
	ds_read_b128 v[242:245], v204 offset:54272
	ds_read_b128 v[246:249], v204 offset:55296
	ds_read_b128 v[250:253], v204 offset:56320
	global_load_lds_dwordx4 v[176:177], off
	s_add_i32 m0, s18, 0x2000
	s_add_u32 s10, s10, 0x40080
	v_lshl_add_u64 v[176:177], v[196:197], 0, s[64:65]
	s_addc_u32 s11, s11, 0
	s_add_i32 s18, s21, s97
	global_load_lds_dwordx4 v[176:177], off
	s_mov_b32 m0, s18
	s_or_b32 s86, s86, 1
	global_load_lds_dwordx4 v132, s[10:11]
	v_lshl_add_u64 v[176:177], s[10:11], 0, v[136:137]
	s_add_i32 m0, s18, 0x2000
	s_lshl_b64 s[10:11], s[86:87], 7
	s_add_u32 s10, s17, s10
	s_addc_u32 s11, s16, s11
	global_load_lds_dwordx4 v[176:177], off
	s_mov_b32 m0, s92
	s_nop 0
	global_load_lds_dwordx4 v130, s[10:11]
	s_mov_b32 m0, s93
	s_nop 0
	global_load_lds_dwordx4 v134, s[10:11]
	s_waitcnt vmcnt(8)
	s_waitcnt lgkmcnt(0)
	s_barrier
	v_mfma_f32_16x16x32_bf16 v[60:63], v[160:163], v[222:225], v[60:63]
	v_mfma_f32_16x16x32_bf16 v[56:59], v[168:171], v[222:225], v[56:59]
	v_mfma_f32_16x16x32_bf16 v[44:47], v[160:163], v[230:233], v[44:47]
	v_mfma_f32_16x16x32_bf16 v[40:43], v[168:171], v[230:233], v[40:43]
	v_mfma_f32_16x16x32_bf16 v[28:31], v[160:163], v[238:241], v[28:31]
	v_mfma_f32_16x16x32_bf16 v[24:27], v[168:171], v[238:241], v[24:27]
	v_mfma_f32_16x16x32_bf16 v[12:15], v[160:163], v[246:249], v[12:15]
	v_mfma_f32_16x16x32_bf16 v[8:11], v[168:171], v[246:249], v[8:11]
	v_mfma_f32_16x16x32_bf16 v[60:63], v[164:167], v[226:229], v[60:63]
	v_mfma_f32_16x16x32_bf16 v[56:59], v[172:175], v[226:229], v[56:59]
	v_mfma_f32_16x16x32_bf16 v[44:47], v[164:167], v[234:237], v[44:47]
	v_mfma_f32_16x16x32_bf16 v[40:43], v[172:175], v[234:237], v[40:43]
	v_mfma_f32_16x16x32_bf16 v[28:31], v[164:167], v[242:245], v[28:31]
	v_mfma_f32_16x16x32_bf16 v[24:27], v[172:175], v[242:245], v[24:27]
	v_mfma_f32_16x16x32_bf16 v[12:15], v[164:167], v[250:253], v[12:15]
	v_mfma_f32_16x16x32_bf16 v[8:11], v[172:175], v[250:253], v[8:11]
	v_mfma_f32_16x16x32_bf16 v[52:55], v[186:189], v[222:225], v[52:55]
	v_mfma_f32_16x16x32_bf16 v[48:51], v[212:215], v[222:225], v[48:51]
	v_mfma_f32_16x16x32_bf16 v[36:39], v[186:189], v[230:233], v[36:39]
	v_mfma_f32_16x16x32_bf16 v[32:35], v[212:215], v[230:233], v[32:35]
	v_mfma_f32_16x16x32_bf16 v[20:23], v[186:189], v[238:241], v[20:23]
	v_mfma_f32_16x16x32_bf16 v[16:19], v[212:215], v[238:241], v[16:19]
	v_mfma_f32_16x16x32_bf16 v[4:7], v[186:189], v[246:249], v[4:7]
	v_mfma_f32_16x16x32_bf16 v[0:3], v[212:215], v[246:249], v[0:3]
	v_mfma_f32_16x16x32_bf16 v[52:55], v[208:211], v[226:229], v[52:55]
	v_mfma_f32_16x16x32_bf16 v[48:51], v[218:221], v[226:229], v[48:51]
	v_mfma_f32_16x16x32_bf16 v[36:39], v[208:211], v[234:237], v[36:39]
	v_mfma_f32_16x16x32_bf16 v[32:35], v[218:221], v[234:237], v[32:35]
	v_mfma_f32_16x16x32_bf16 v[20:23], v[208:211], v[242:245], v[20:23]
	v_mfma_f32_16x16x32_bf16 v[16:19], v[218:221], v[242:245], v[16:19]
	v_mfma_f32_16x16x32_bf16 v[4:7], v[208:211], v[250:253], v[4:7]
	v_mfma_f32_16x16x32_bf16 v[0:3], v[218:221], v[250:253], v[0:3]
	s_barrier
	s_add_u32 s6, s6, 0x100
	s_addc_u32 s7, s7, 0
	s_cmp_gt_u32 s14, 13
	s_mov_b32 s14, s15
	s_cbranch_scc0 .LBB0_124
	s_and_b64 vcc, exec, s[66:67]
	s_cbranch_vccz .LBB0_127
	s_barrier

.LBB0_425:
	s_add_u32 s12, s30, s38
	s_addc_u32 s42, s31, s39
	s_add_u32 s12, s12, 0xfff80080
	s_addc_u32 s65, s42, -1
	s_cmp_eq_u32 s64, 30
	s_cselect_b64 s[42:43], -1, 0
	s_and_b64 s[42:43], s[42:43], exec
	s_cselect_b32 s43, s19, s65
	s_cselect_b32 s42, s21, s12
	s_add_i32 s65, s64, 2
	s_cmp_eq_u32 s64, 30
	s_cselect_b64 s[66:67], -1, 0
	s_and_b64 s[68:69], s[66:67], exec
	s_cselect_b32 s12, 0, s65
	s_and_b64 s[66:67], s[66:67], s[4:5]
	s_and_b64 s[66:67], s[66:67], exec
	s_cselect_b32 s68, s23, s35
	s_cselect_b32 s69, s22, s34
	s_cselect_b32 s66, s27, s37
	s_cselect_b32 s67, s26, s36
	v_lshl_add_u64 v[214:215], s[44:45], 0, v[214:215]
	s_add_i32 m0, s29, 0xc000
	v_lshl_add_u64 v[2:3], s[44:45], 0, v[2:3]
	global_load_lds_dwordx4 v[214:215], off
	s_add_i32 m0, s29, 0xe000
	s_nop 0
	global_load_lds_dwordx4 v[2:3], off
	s_waitcnt vmcnt(8)
	s_waitcnt lgkmcnt(0)
	s_barrier
	v_mfma_f32_16x16x32_bf16 v[128:131], v[148:151], v[188:191], v[128:131]
	v_mfma_f32_16x16x32_bf16 v[124:127], v[156:159], v[188:191], v[124:127]
	v_mfma_f32_16x16x32_bf16 v[112:115], v[148:151], v[180:183], v[112:115]
	v_mfma_f32_16x16x32_bf16 v[108:111], v[156:159], v[180:183], v[108:111]
	v_mfma_f32_16x16x32_bf16 v[96:99], v[148:151], v[172:175], v[96:99]
	v_mfma_f32_16x16x32_bf16 v[92:95], v[156:159], v[172:175], v[92:95]
	v_mfma_f32_16x16x32_bf16 v[80:83], v[148:151], v[164:167], v[80:83]
	v_mfma_f32_16x16x32_bf16 v[76:79], v[156:159], v[164:167], v[76:79]
	v_mfma_f32_16x16x32_bf16 v[128:131], v[152:155], v[192:195], v[128:131]
	v_mfma_f32_16x16x32_bf16 v[124:127], v[160:163], v[192:195], v[124:127]
	v_mfma_f32_16x16x32_bf16 v[112:115], v[152:155], v[184:187], v[112:115]
	v_mfma_f32_16x16x32_bf16 v[108:111], v[160:163], v[184:187], v[108:111]
	v_mfma_f32_16x16x32_bf16 v[96:99], v[152:155], v[176:179], v[96:99]
	v_mfma_f32_16x16x32_bf16 v[92:95], v[160:163], v[176:179], v[92:95]
	v_mfma_f32_16x16x32_bf16 v[80:83], v[152:155], v[168:171], v[80:83]
	v_mfma_f32_16x16x32_bf16 v[76:79], v[160:163], v[168:171], v[76:79]
	v_mfma_f32_16x16x32_bf16 v[120:123], v[132:135], v[188:191], v[120:123]
	v_mfma_f32_16x16x32_bf16 v[116:119], v[140:143], v[188:191], v[116:119]
	v_mfma_f32_16x16x32_bf16 v[104:107], v[132:135], v[180:183], v[104:107]
	v_mfma_f32_16x16x32_bf16 v[100:103], v[140:143], v[180:183], v[100:103]
	v_mfma_f32_16x16x32_bf16 v[88:91], v[132:135], v[172:175], v[88:91]
	v_mfma_f32_16x16x32_bf16 v[84:87], v[140:143], v[172:175], v[84:87]
	v_mfma_f32_16x16x32_bf16 v[72:75], v[132:135], v[164:167], v[72:75]
	v_mfma_f32_16x16x32_bf16 v[68:71], v[140:143], v[164:167], v[68:71]
	v_mfma_f32_16x16x32_bf16 v[120:123], v[136:139], v[192:195], v[120:123]
	v_mfma_f32_16x16x32_bf16 v[116:119], v[144:147], v[192:195], v[116:119]
	v_mfma_f32_16x16x32_bf16 v[104:107], v[136:139], v[184:187], v[104:107]
	v_mfma_f32_16x16x32_bf16 v[100:103], v[144:147], v[184:187], v[100:103]
	v_mfma_f32_16x16x32_bf16 v[88:91], v[136:139], v[176:179], v[88:91]
	v_mfma_f32_16x16x32_bf16 v[84:87], v[144:147], v[176:179], v[84:87]
	v_mfma_f32_16x16x32_bf16 v[72:75], v[136:139], v[168:171], v[72:75]
	v_mfma_f32_16x16x32_bf16 v[68:71], v[144:147], v[168:171], v[68:71]
	s_barrier
	s_mov_b32 m0, s47
	v_lshl_add_u64 v[214:215], s[42:43], 0, v[198:199]
	s_add_u32 s44, s42, 0x80000
	ds_read_b128 v[164:167], v219 offset:16384
	ds_read_b128 v[168:171], v219 offset:17408
	ds_read_b128 v[172:175], v219 offset:18432
	ds_read_b128 v[176:179], v219 offset:19456
	ds_read_b128 v[180:183], v219 offset:20480
	ds_read_b128 v[184:187], v219 offset:21504
	ds_read_b128 v[188:191], v219 offset:22528
	ds_read_b128 v[192:195], v219 offset:23552
	global_load_lds_dwordx4 v[214:215], off
	v_lshl_add_u64 v[220:221], s[42:43], 0, v[202:203]
	s_mov_b32 m0, s48
	s_addc_u32 s45, s43, 0
	global_load_lds_dwordx4 v[220:221], off
	v_lshl_add_u64 v[2:3], s[44:45], 0, v[198:199]
	s_mov_b32 m0, s49
	s_add_i32 s70, s12, -8
	global_load_lds_dwordx4 v[2:3], off
	v_lshl_add_u64 v[2:3], s[44:45], 0, v[202:203]
	s_lshl_b64 s[44:45], s[12:13], 7
	s_add_u32 s71, s69, s44
	s_addc_u32 s72, s68, s45
	s_lshl_b32 s44, s70, 19
	s_add_u32 s73, s67, s44
	s_addc_u32 s74, s66, 0
	s_add_i32 s75, 0, 0x18000
	s_add_i32 s76, 0, 0x1c000
	s_add_u32 s77, s71, 0x80000
	s_addc_u32 s84, s72, 0
	s_add_u32 s85, s73, 0x800
	s_addc_u32 s86, s74, 0
	s_cmp_lt_u32 s70, 16
	s_cselect_b64 vcc, -1, 0
	s_and_b64 s[44:45], vcc, exec
	s_mov_b32 m0, s50
	v_cndmask_b32_e32 v222, v196, v204, vcc
	v_mov_b32_e32 v223, v1
	s_cselect_b32 s45, s74, s72
	s_cselect_b32 s44, s73, s71
	global_load_lds_dwordx4 v[2:3], off
	v_cndmask_b32_e32 v0, v200, v206, vcc
	v_lshl_add_u64 v[2:3], s[44:45], 0, v[222:223]
	s_mov_b32 m0, s29
	s_nop 0
	global_load_lds_dwordx4 v[2:3], off
	v_lshl_add_u64 v[2:3], s[44:45], 0, v[0:1]
	s_mov_b32 m0, s51
	s_nop 0
	global_load_lds_dwordx4 v[2:3], off
	s_waitcnt vmcnt(8)
	s_waitcnt lgkmcnt(0)
	s_barrier
	v_mfma_f32_16x16x32_bf16 v[64:67], v[148:151], v[164:167], v[64:67]
	v_mfma_f32_16x16x32_bf16 v[60:63], v[156:159], v[164:167], v[60:63]
	v_mfma_f32_16x16x32_bf16 v[48:51], v[148:151], v[172:175], v[48:51]
	v_mfma_f32_16x16x32_bf16 v[44:47], v[156:159], v[172:175], v[44:47]
	v_mfma_f32_16x16x32_bf16 v[32:35], v[148:151], v[180:183], v[32:35]
	v_mfma_f32_16x16x32_bf16 v[28:31], v[156:159], v[180:183], v[28:31]
	v_mfma_f32_16x16x32_bf16 v[16:19], v[148:151], v[188:191], v[16:19]
	v_mfma_f32_16x16x32_bf16 v[12:15], v[156:159], v[188:191], v[12:15]
	v_mfma_f32_16x16x32_bf16 v[64:67], v[152:155], v[168:171], v[64:67]
	v_mfma_f32_16x16x32_bf16 v[60:63], v[160:163], v[168:171], v[60:63]
	v_mfma_f32_16x16x32_bf16 v[48:51], v[152:155], v[176:179], v[48:51]
	v_mfma_f32_16x16x32_bf16 v[44:47], v[160:163], v[176:179], v[44:47]
	v_mfma_f32_16x16x32_bf16 v[32:35], v[152:155], v[184:187], v[32:35]
	v_mfma_f32_16x16x32_bf16 v[28:31], v[160:163], v[184:187], v[28:31]
	v_mfma_f32_16x16x32_bf16 v[16:19], v[152:155], v[192:195], v[16:19]
	v_mfma_f32_16x16x32_bf16 v[12:15], v[160:163], v[192:195], v[12:15]
	v_mfma_f32_16x16x32_bf16 v[56:59], v[132:135], v[164:167], v[56:59]
	v_mfma_f32_16x16x32_bf16 v[52:55], v[140:143], v[164:167], v[52:55]
	v_mfma_f32_16x16x32_bf16 v[40:43], v[132:135], v[172:175], v[40:43]
	v_mfma_f32_16x16x32_bf16 v[36:39], v[140:143], v[172:175], v[36:39]
	v_mfma_f32_16x16x32_bf16 v[24:27], v[132:135], v[180:183], v[24:27]
	v_mfma_f32_16x16x32_bf16 v[20:23], v[140:143], v[180:183], v[20:23]
	v_mfma_f32_16x16x32_bf16 v[8:11], v[132:135], v[188:191], v[8:11]
	v_mfma_f32_16x16x32_bf16 v[2:5], v[140:143], v[188:191], v[4:7]
	v_mfma_f32_16x16x32_bf16 v[56:59], v[136:139], v[168:171], v[56:59]
	v_mfma_f32_16x16x32_bf16 v[52:55], v[144:147], v[168:171], v[52:55]
	v_mfma_f32_16x16x32_bf16 v[40:43], v[136:139], v[176:179], v[40:43]
	v_mfma_f32_16x16x32_bf16 v[36:39], v[144:147], v[176:179], v[36:39]
	v_mfma_f32_16x16x32_bf16 v[24:27], v[136:139], v[184:187], v[24:27]
	v_mfma_f32_16x16x32_bf16 v[20:23], v[144:147], v[184:187], v[20:23]
	v_mfma_f32_16x16x32_bf16 v[8:11], v[136:139], v[192:195], v[8:11]
	v_mfma_f32_16x16x32_bf16 v[2:5], v[144:147], v[192:195], v[2:5]
	s_barrier
	v_add_u32_e32 v6, s75, v217
	ds_read_b128 v[148:151], v6
	ds_read_b128 v[152:155], v6 offset:1024
	ds_read_b128 v[156:159], v6 offset:2048
	ds_read_b128 v[160:163], v6 offset:3072
	v_add_u32_e32 v6, s76, v217
	ds_read_b128 v[132:135], v6
	ds_read_b128 v[136:139], v6 offset:1024
	ds_read_b128 v[140:143], v6 offset:2048
	ds_read_b128 v[144:147], v6 offset:3072
	s_cselect_b32 s45, s86, s84
	s_cselect_b32 s44, s85, s77
	s_mov_b32 m0, s52
	v_lshl_add_u64 v[6:7], s[44:45], 0, v[222:223]
	ds_read_b128 v[164:167], v219 offset:32768
	ds_read_b128 v[168:171], v219 offset:33792
	ds_read_b128 v[172:175], v219 offset:34816
	ds_read_b128 v[176:179], v219 offset:35840
	ds_read_b128 v[180:183], v219 offset:36864
	ds_read_b128 v[184:187], v219 offset:37888
	ds_read_b128 v[188:191], v219 offset:38912
	ds_read_b128 v[192:195], v219 offset:39936
	global_load_lds_dwordx4 v[6:7], off
	v_lshl_add_u64 v[6:7], s[44:45], 0, v[0:1]
	s_mov_b32 m0, s53
	s_nop 0
	global_load_lds_dwordx4 v[6:7], off
	s_waitcnt vmcnt(8)
	s_waitcnt lgkmcnt(0)
	s_barrier
	v_mfma_f32_16x16x32_bf16 v[128:131], v[148:151], v[164:167], v[128:131]
	v_mfma_f32_16x16x32_bf16 v[124:127], v[156:159], v[164:167], v[124:127]
	v_mfma_f32_16x16x32_bf16 v[112:115], v[148:151], v[172:175], v[112:115]
	v_mfma_f32_16x16x32_bf16 v[108:111], v[156:159], v[172:175], v[108:111]
	v_mfma_f32_16x16x32_bf16 v[96:99], v[148:151], v[180:183], v[96:99]
	v_mfma_f32_16x16x32_bf16 v[92:95], v[156:159], v[180:183], v[92:95]
	v_mfma_f32_16x16x32_bf16 v[80:83], v[148:151], v[188:191], v[80:83]
	v_mfma_f32_16x16x32_bf16 v[76:79], v[156:159], v[188:191], v[76:79]
	v_mfma_f32_16x16x32_bf16 v[128:131], v[152:155], v[168:171], v[128:131]
	v_mfma_f32_16x16x32_bf16 v[124:127], v[160:163], v[168:171], v[124:127]
	v_mfma_f32_16x16x32_bf16 v[112:115], v[152:155], v[176:179], v[112:115]
	v_mfma_f32_16x16x32_bf16 v[108:111], v[160:163], v[176:179], v[108:111]
	v_mfma_f32_16x16x32_bf16 v[96:99], v[152:155], v[184:187], v[96:99]
	v_mfma_f32_16x16x32_bf16 v[92:95], v[160:163], v[184:187], v[92:95]
	v_mfma_f32_16x16x32_bf16 v[80:83], v[152:155], v[192:195], v[80:83]
	v_mfma_f32_16x16x32_bf16 v[76:79], v[160:163], v[192:195], v[76:79]
	v_mfma_f32_16x16x32_bf16 v[120:123], v[132:135], v[164:167], v[120:123]
	v_mfma_f32_16x16x32_bf16 v[116:119], v[140:143], v[164:167], v[116:119]
	v_mfma_f32_16x16x32_bf16 v[104:107], v[132:135], v[172:175], v[104:107]
	v_mfma_f32_16x16x32_bf16 v[100:103], v[140:143], v[172:175], v[100:103]
	v_mfma_f32_16x16x32_bf16 v[88:91], v[132:135], v[180:183], v[88:91]
	v_mfma_f32_16x16x32_bf16 v[84:87], v[140:143], v[180:183], v[84:87]
	v_mfma_f32_16x16x32_bf16 v[72:75], v[132:135], v[188:191], v[72:75]
	v_mfma_f32_16x16x32_bf16 v[68:71], v[140:143], v[188:191], v[68:71]
	v_mfma_f32_16x16x32_bf16 v[120:123], v[136:139], v[168:171], v[120:123]
	v_mfma_f32_16x16x32_bf16 v[116:119], v[144:147], v[168:171], v[116:119]
	v_mfma_f32_16x16x32_bf16 v[104:107], v[136:139], v[176:179], v[104:107]
	v_mfma_f32_16x16x32_bf16 v[100:103], v[144:147], v[176:179], v[100:103]
	v_mfma_f32_16x16x32_bf16 v[88:91], v[136:139], v[184:187], v[88:91]
	v_mfma_f32_16x16x32_bf16 v[84:87], v[144:147], v[184:187], v[84:87]
	v_mfma_f32_16x16x32_bf16 v[72:75], v[136:139], v[192:195], v[72:75]
	v_mfma_f32_16x16x32_bf16 v[68:71], v[144:147], v[192:195], v[68:71]
	s_barrier
	s_add_i32 s44, s75, s33
	v_lshl_add_u64 v[6:7], v[214:215], 0, s[14:15]
	s_mov_b32 m0, s44
	ds_read_b128 v[188:191], v219 offset:49152
	ds_read_b128 v[192:195], v219 offset:50176
	ds_read_b128 v[180:183], v219 offset:51200
	ds_read_b128 v[184:187], v219 offset:52224
	ds_read_b128 v[172:175], v219 offset:53248
	ds_read_b128 v[176:179], v219 offset:54272
	ds_read_b128 v[164:167], v219 offset:55296
	ds_read_b128 v[168:171], v219 offset:56320
	global_load_lds_dwordx4 v[6:7], off
	s_add_i32 m0, s44, 0x2000
	s_add_u32 s42, s42, 0x80080
	v_lshl_add_u64 v[6:7], v[220:221], 0, s[14:15]
	s_addc_u32 s43, s43, 0
	s_add_i32 s44, s76, s33
	global_load_lds_dwordx4 v[6:7], off
	v_lshl_add_u64 v[6:7], s[42:43], 0, v[198:199]
	s_mov_b32 m0, s44
	s_add_i32 s70, s12, -7
	global_load_lds_dwordx4 v[6:7], off
	v_lshl_add_u64 v[6:7], s[42:43], 0, v[202:203]
	s_add_i32 m0, s44, 0x2000
	s_cmp_gt_u32 s70, 15
	global_load_lds_dwordx4 v[6:7], off
	s_mov_b64 s[44:45], -1
	s_cbranch_scc0 .LBB0_427
	s_or_b32 s12, s12, 1
	s_lshl_b64 s[42:43], s[12:13], 7
	s_add_u32 s42, s69, s42
	s_addc_u32 s43, s68, s43
	s_mov_b64 s[44:45], 0

.LBB0_429:
	s_mov_b32 m0, s55
	v_lshl_add_u64 v[214:215], s[42:43], 0, v[214:215]
	global_load_lds_dwordx4 v[214:215], off
	v_lshl_add_u64 v[6:7], s[42:43], 0, v[6:7]
	s_mov_b32 m0, s56
	s_nop 0
	global_load_lds_dwordx4 v[6:7], off
	s_waitcnt vmcnt(8)
	s_waitcnt lgkmcnt(0)
	s_barrier
	v_mfma_f32_16x16x32_bf16 v[64:67], v[148:151], v[188:191], v[64:67]
	v_mfma_f32_16x16x32_bf16 v[60:63], v[156:159], v[188:191], v[60:63]
	v_mfma_f32_16x16x32_bf16 v[48:51], v[148:151], v[180:183], v[48:51]
	v_mfma_f32_16x16x32_bf16 v[44:47], v[156:159], v[180:183], v[44:47]
	v_mfma_f32_16x16x32_bf16 v[32:35], v[148:151], v[172:175], v[32:35]
	v_mfma_f32_16x16x32_bf16 v[28:31], v[156:159], v[172:175], v[28:31]
	v_mfma_f32_16x16x32_bf16 v[16:19], v[148:151], v[164:167], v[16:19]
	v_mfma_f32_16x16x32_bf16 v[12:15], v[156:159], v[164:167], v[12:15]
	v_mfma_f32_16x16x32_bf16 v[64:67], v[152:155], v[192:195], v[64:67]
	v_mfma_f32_16x16x32_bf16 v[60:63], v[160:163], v[192:195], v[60:63]
	v_mfma_f32_16x16x32_bf16 v[48:51], v[152:155], v[184:187], v[48:51]
	v_mfma_f32_16x16x32_bf16 v[44:47], v[160:163], v[184:187], v[44:47]
	v_mfma_f32_16x16x32_bf16 v[32:35], v[152:155], v[176:179], v[32:35]
	v_mfma_f32_16x16x32_bf16 v[28:31], v[160:163], v[176:179], v[28:31]
	v_mfma_f32_16x16x32_bf16 v[16:19], v[152:155], v[168:171], v[16:19]
	v_mfma_f32_16x16x32_bf16 v[12:15], v[160:163], v[168:171], v[12:15]
	v_mfma_f32_16x16x32_bf16 v[56:59], v[132:135], v[188:191], v[56:59]
	v_mfma_f32_16x16x32_bf16 v[52:55], v[140:143], v[188:191], v[52:55]
	v_mfma_f32_16x16x32_bf16 v[40:43], v[132:135], v[180:183], v[40:43]
	v_mfma_f32_16x16x32_bf16 v[36:39], v[140:143], v[180:183], v[36:39]
	v_mfma_f32_16x16x32_bf16 v[24:27], v[132:135], v[172:175], v[24:27]
	v_mfma_f32_16x16x32_bf16 v[20:23], v[140:143], v[172:175], v[20:23]
	v_mfma_f32_16x16x32_bf16 v[6:9], v[132:135], v[164:167], v[8:11]
	v_mfma_f32_16x16x32_bf16 v[2:5], v[140:143], v[164:167], v[2:5]
	v_mfma_f32_16x16x32_bf16 v[56:59], v[136:139], v[192:195], v[56:59]
	v_mfma_f32_16x16x32_bf16 v[52:55], v[144:147], v[192:195], v[52:55]
	v_mfma_f32_16x16x32_bf16 v[40:43], v[136:139], v[184:187], v[40:43]
	v_mfma_f32_16x16x32_bf16 v[36:39], v[144:147], v[184:187], v[36:39]
	v_mfma_f32_16x16x32_bf16 v[24:27], v[136:139], v[176:179], v[24:27]
	v_mfma_f32_16x16x32_bf16 v[20:23], v[144:147], v[176:179], v[20:23]
	v_mfma_f32_16x16x32_bf16 v[8:11], v[136:139], v[168:171], v[6:9]
	v_mfma_f32_16x16x32_bf16 v[4:7], v[144:147], v[168:171], v[2:5]
	s_barrier
	s_add_u32 s38, s38, 0x100
	s_addc_u32 s39, s39, 0
	s_add_i32 s63, s63, 0x100000
	s_cmp_gt_u32 s64, 29
	s_cbranch_scc1 .LBB0_408
	s_mov_b32 s64, s65
	s_cmp_lt_i32 s64, 24
	s_cbranch_scc1 .LBB0_417
	s_branch .LBB0_416

.LBB0_504:
	s_add_u32 s20, s31, s44
	ds_read_b128 v[132:135], v217
	ds_read_b128 v[136:139], v217 offset:1024
	ds_read_b128 v[140:143], v217 offset:2048
	ds_read_b128 v[144:147], v217 offset:3072
	ds_read_b128 v[148:151], v218
	ds_read_b128 v[152:155], v218 offset:1024
	ds_read_b128 v[156:159], v218 offset:2048
	ds_read_b128 v[160:163], v218 offset:3072
	s_addc_u32 s48, s39, s45
	s_cmpk_eq_i32 s44, 0x700
	s_cselect_b64 s[46:47], -1, 0
	s_and_b64 s[46:47], s[46:47], exec
	s_cselect_b32 s47, s19, s48
	s_cselect_b32 s46, s29, s20
	s_add_i32 s64, s63, 2
	s_cmpk_eq_i32 s44, 0x700
	s_cselect_b64 s[48:49], -1, 0
	s_and_b64 s[66:67], s[48:49], exec
	s_cselect_b32 s20, 0, s64
	s_and_b64 s[48:49], s[48:49], s[6:7]
	s_and_b64 s[48:49], s[48:49], exec
	s_cselect_b32 s48, s35, s43
	s_cselect_b32 s49, s34, s42
	v_lshl_add_u64 v[238:239], v[128:129], 0, s[44:45]
	s_add_i32 m0, s50, 0xc000
	ds_read_b128 v[164:167], v219
	ds_read_b128 v[168:171], v219 offset:1024
	ds_read_b128 v[172:175], v219 offset:2048
	ds_read_b128 v[192:195], v219 offset:3072
	ds_read_b128 v[222:225], v219 offset:4096
	ds_read_b128 v[226:229], v219 offset:5120
	ds_read_b128 v[230:233], v219 offset:6144
	ds_read_b128 v[234:237], v219 offset:7168
	global_load_lds_dwordx4 v[238:239], off
	v_lshl_add_u64 v[238:239], v[130:131], 0, s[44:45]
	s_add_i32 m0, s50, 0xe000
	s_nop 0
	global_load_lds_dwordx4 v[238:239], off
	s_waitcnt vmcnt(8)
	s_waitcnt lgkmcnt(0)
	s_barrier
	v_mfma_f32_16x16x32_bf16 v[124:127], v[132:135], v[164:167], v[124:127]
	v_mfma_f32_16x16x32_bf16 v[120:123], v[140:143], v[164:167], v[120:123]
	v_mfma_f32_16x16x32_bf16 v[108:111], v[132:135], v[172:175], v[108:111]
	v_mfma_f32_16x16x32_bf16 v[104:107], v[140:143], v[172:175], v[104:107]
	v_mfma_f32_16x16x32_bf16 v[92:95], v[132:135], v[222:225], v[92:95]
	v_mfma_f32_16x16x32_bf16 v[88:91], v[140:143], v[222:225], v[88:91]
	v_mfma_f32_16x16x32_bf16 v[76:79], v[132:135], v[230:233], v[76:79]
	v_mfma_f32_16x16x32_bf16 v[72:75], v[140:143], v[230:233], v[72:75]
	v_mfma_f32_16x16x32_bf16 v[124:127], v[136:139], v[168:171], v[124:127]
	v_mfma_f32_16x16x32_bf16 v[120:123], v[144:147], v[168:171], v[120:123]
	v_mfma_f32_16x16x32_bf16 v[108:111], v[136:139], v[192:195], v[108:111]
	v_mfma_f32_16x16x32_bf16 v[104:107], v[144:147], v[192:195], v[104:107]
	v_mfma_f32_16x16x32_bf16 v[92:95], v[136:139], v[226:229], v[92:95]
	v_mfma_f32_16x16x32_bf16 v[88:91], v[144:147], v[226:229], v[88:91]
	v_mfma_f32_16x16x32_bf16 v[76:79], v[136:139], v[234:237], v[76:79]
	v_mfma_f32_16x16x32_bf16 v[72:75], v[144:147], v[234:237], v[72:75]
	v_mfma_f32_16x16x32_bf16 v[116:119], v[148:151], v[164:167], v[116:119]
	v_mfma_f32_16x16x32_bf16 v[112:115], v[156:159], v[164:167], v[112:115]
	v_mfma_f32_16x16x32_bf16 v[100:103], v[148:151], v[172:175], v[100:103]
	v_mfma_f32_16x16x32_bf16 v[96:99], v[156:159], v[172:175], v[96:99]
	v_mfma_f32_16x16x32_bf16 v[84:87], v[148:151], v[222:225], v[84:87]
	v_mfma_f32_16x16x32_bf16 v[80:83], v[156:159], v[222:225], v[80:83]
	v_mfma_f32_16x16x32_bf16 v[68:71], v[148:151], v[230:233], v[68:71]
	v_mfma_f32_16x16x32_bf16 v[64:67], v[156:159], v[230:233], v[64:67]
	v_mfma_f32_16x16x32_bf16 v[116:119], v[152:155], v[168:171], v[116:119]
	v_mfma_f32_16x16x32_bf16 v[112:115], v[160:163], v[168:171], v[112:115]
	v_mfma_f32_16x16x32_bf16 v[100:103], v[152:155], v[192:195], v[100:103]
	v_mfma_f32_16x16x32_bf16 v[96:99], v[160:163], v[192:195], v[96:99]
	v_mfma_f32_16x16x32_bf16 v[84:87], v[152:155], v[226:229], v[84:87]
	v_mfma_f32_16x16x32_bf16 v[80:83], v[160:163], v[226:229], v[80:83]
	v_mfma_f32_16x16x32_bf16 v[68:71], v[152:155], v[234:237], v[68:71]
	v_mfma_f32_16x16x32_bf16 v[64:67], v[160:163], v[234:237], v[64:67]
	s_barrier
	s_add_i32 s65, s58, s33
	v_lshl_add_u64 v[238:239], s[46:47], 0, v[178:179]
	s_mov_b32 m0, s65
	ds_read_b128 v[164:167], v219 offset:16384
	ds_read_b128 v[168:171], v219 offset:17408
	ds_read_b128 v[172:175], v219 offset:18432
	ds_read_b128 v[192:195], v219 offset:19456
	ds_read_b128 v[222:225], v219 offset:20480
	ds_read_b128 v[226:229], v219 offset:21504
	ds_read_b128 v[230:233], v219 offset:22528
	ds_read_b128 v[234:237], v219 offset:23552
	global_load_lds_dwordx4 v[238:239], off
	s_add_i32 m0, s65, 0x2000
	s_add_u32 s66, s46, 0x40000
	v_lshl_add_u64 v[240:241], s[46:47], 0, v[182:183]
	s_addc_u32 s67, s47, 0
	s_add_i32 s65, s59, s33
	global_load_lds_dwordx4 v[240:241], off
	v_lshl_add_u64 v[242:243], s[66:67], 0, v[178:179]
	s_mov_b32 m0, s65
	s_nop 0
	global_load_lds_dwordx4 v[242:243], off
	v_lshl_add_u64 v[242:243], s[66:67], 0, v[182:183]
	s_add_i32 m0, s65, 0x2000
	s_lshl_b64 s[66:67], s[20:21], 7
	s_add_u32 s66, s49, s66
	s_addc_u32 s67, s48, s67
	global_load_lds_dwordx4 v[242:243], off
	v_lshl_add_u64 v[242:243], s[66:67], 0, v[176:177]
	s_mov_b32 m0, s50
	s_nop 0
	global_load_lds_dwordx4 v[242:243], off
	v_lshl_add_u64 v[242:243], s[66:67], 0, v[180:181]
	s_mov_b32 m0, s51
	s_nop 0
	global_load_lds_dwordx4 v[242:243], off
	s_waitcnt vmcnt(8)
	s_waitcnt lgkmcnt(0)
	s_barrier
	v_mfma_f32_16x16x32_bf16 v[60:63], v[132:135], v[164:167], v[60:63]
	v_mfma_f32_16x16x32_bf16 v[56:59], v[140:143], v[164:167], v[56:59]
	v_mfma_f32_16x16x32_bf16 v[44:47], v[132:135], v[172:175], v[44:47]
	v_mfma_f32_16x16x32_bf16 v[40:43], v[140:143], v[172:175], v[40:43]
	v_mfma_f32_16x16x32_bf16 v[28:31], v[132:135], v[222:225], v[28:31]
	v_mfma_f32_16x16x32_bf16 v[24:27], v[140:143], v[222:225], v[24:27]
	v_mfma_f32_16x16x32_bf16 v[12:15], v[132:135], v[230:233], v[12:15]
	v_mfma_f32_16x16x32_bf16 v[8:11], v[140:143], v[230:233], v[8:11]
	v_mfma_f32_16x16x32_bf16 v[60:63], v[136:139], v[168:171], v[60:63]
	v_mfma_f32_16x16x32_bf16 v[56:59], v[144:147], v[168:171], v[56:59]
	v_mfma_f32_16x16x32_bf16 v[44:47], v[136:139], v[192:195], v[44:47]
	v_mfma_f32_16x16x32_bf16 v[40:43], v[144:147], v[192:195], v[40:43]
	v_mfma_f32_16x16x32_bf16 v[28:31], v[136:139], v[226:229], v[28:31]
	v_mfma_f32_16x16x32_bf16 v[24:27], v[144:147], v[226:229], v[24:27]
	v_mfma_f32_16x16x32_bf16 v[12:15], v[136:139], v[234:237], v[12:15]
	v_mfma_f32_16x16x32_bf16 v[8:11], v[144:147], v[234:237], v[8:11]
	v_mfma_f32_16x16x32_bf16 v[52:55], v[148:151], v[164:167], v[52:55]
	v_mfma_f32_16x16x32_bf16 v[48:51], v[156:159], v[164:167], v[48:51]
	v_mfma_f32_16x16x32_bf16 v[36:39], v[148:151], v[172:175], v[36:39]
	v_mfma_f32_16x16x32_bf16 v[32:35], v[156:159], v[172:175], v[32:35]
	v_mfma_f32_16x16x32_bf16 v[20:23], v[148:151], v[222:225], v[20:23]
	v_mfma_f32_16x16x32_bf16 v[16:19], v[156:159], v[222:225], v[16:19]
	v_mfma_f32_16x16x32_bf16 v[4:7], v[148:151], v[230:233], v[4:7]
	v_mfma_f32_16x16x32_bf16 v[0:3], v[156:159], v[230:233], v[0:3]
	v_mfma_f32_16x16x32_bf16 v[52:55], v[152:155], v[168:171], v[52:55]
	v_mfma_f32_16x16x32_bf16 v[48:51], v[160:163], v[168:171], v[48:51]
	v_mfma_f32_16x16x32_bf16 v[36:39], v[152:155], v[192:195], v[36:39]
	v_mfma_f32_16x16x32_bf16 v[32:35], v[160:163], v[192:195], v[32:35]
	v_mfma_f32_16x16x32_bf16 v[20:23], v[152:155], v[226:229], v[20:23]
	v_mfma_f32_16x16x32_bf16 v[16:19], v[160:163], v[226:229], v[16:19]
	v_mfma_f32_16x16x32_bf16 v[4:7], v[152:155], v[234:237], v[4:7]
	v_mfma_f32_16x16x32_bf16 v[0:3], v[160:163], v[234:237], v[0:3]
	s_barrier
	s_add_i32 s65, 0, 0x18000
	s_add_i32 s68, 0, 0x1c000
	v_add_u32_e32 v144, s65, v198
	v_add_u32_e32 v160, s68, v198
	ds_read_b128 v[132:135], v144
	ds_read_b128 v[136:139], v144 offset:1024
	ds_read_b128 v[140:143], v144 offset:2048
	ds_read_b128 v[144:147], v144 offset:3072
	ds_read_b128 v[148:151], v160
	ds_read_b128 v[152:155], v160 offset:1024
	ds_read_b128 v[156:159], v160 offset:2048
	ds_read_b128 v[160:163], v160 offset:3072
	s_add_u32 s66, s66, 0x40000
	s_addc_u32 s67, s67, 0
	s_mov_b32 m0, s52
	v_lshl_add_u64 v[242:243], s[66:67], 0, v[176:177]
	ds_read_b128 v[164:167], v219 offset:32768
	ds_read_b128 v[168:171], v219 offset:33792
	ds_read_b128 v[172:175], v219 offset:34816
	ds_read_b128 v[192:195], v219 offset:35840
	ds_read_b128 v[222:225], v219 offset:36864
	ds_read_b128 v[226:229], v219 offset:37888
	ds_read_b128 v[230:233], v219 offset:38912
	ds_read_b128 v[234:237], v219 offset:39936
	global_load_lds_dwordx4 v[242:243], off
	v_lshl_add_u64 v[242:243], s[66:67], 0, v[180:181]
	s_mov_b32 m0, s53
	s_nop 0
	global_load_lds_dwordx4 v[242:243], off
	s_waitcnt vmcnt(8)
	s_waitcnt lgkmcnt(0)
	s_barrier
	v_mfma_f32_16x16x32_bf16 v[124:127], v[132:135], v[164:167], v[124:127]
	v_mfma_f32_16x16x32_bf16 v[120:123], v[140:143], v[164:167], v[120:123]
	v_mfma_f32_16x16x32_bf16 v[108:111], v[132:135], v[172:175], v[108:111]
	v_mfma_f32_16x16x32_bf16 v[104:107], v[140:143], v[172:175], v[104:107]
	v_mfma_f32_16x16x32_bf16 v[92:95], v[132:135], v[222:225], v[92:95]
	v_mfma_f32_16x16x32_bf16 v[88:91], v[140:143], v[222:225], v[88:91]
	v_mfma_f32_16x16x32_bf16 v[76:79], v[132:135], v[230:233], v[76:79]
	v_mfma_f32_16x16x32_bf16 v[72:75], v[140:143], v[230:233], v[72:75]
	v_mfma_f32_16x16x32_bf16 v[124:127], v[136:139], v[168:171], v[124:127]
	v_mfma_f32_16x16x32_bf16 v[120:123], v[144:147], v[168:171], v[120:123]
	v_mfma_f32_16x16x32_bf16 v[108:111], v[136:139], v[192:195], v[108:111]
	v_mfma_f32_16x16x32_bf16 v[104:107], v[144:147], v[192:195], v[104:107]
	v_mfma_f32_16x16x32_bf16 v[92:95], v[136:139], v[226:229], v[92:95]
	v_mfma_f32_16x16x32_bf16 v[88:91], v[144:147], v[226:229], v[88:91]
	v_mfma_f32_16x16x32_bf16 v[76:79], v[136:139], v[234:237], v[76:79]
	v_mfma_f32_16x16x32_bf16 v[72:75], v[144:147], v[234:237], v[72:75]
	v_mfma_f32_16x16x32_bf16 v[116:119], v[148:151], v[164:167], v[116:119]
	v_mfma_f32_16x16x32_bf16 v[112:115], v[156:159], v[164:167], v[112:115]
	v_mfma_f32_16x16x32_bf16 v[100:103], v[148:151], v[172:175], v[100:103]
	v_mfma_f32_16x16x32_bf16 v[96:99], v[156:159], v[172:175], v[96:99]
	v_mfma_f32_16x16x32_bf16 v[84:87], v[148:151], v[222:225], v[84:87]
	v_mfma_f32_16x16x32_bf16 v[80:83], v[156:159], v[222:225], v[80:83]
	v_mfma_f32_16x16x32_bf16 v[68:71], v[148:151], v[230:233], v[68:71]
	v_mfma_f32_16x16x32_bf16 v[64:67], v[156:159], v[230:233], v[64:67]
	v_mfma_f32_16x16x32_bf16 v[116:119], v[152:155], v[168:171], v[116:119]
	v_mfma_f32_16x16x32_bf16 v[112:115], v[160:163], v[168:171], v[112:115]
	v_mfma_f32_16x16x32_bf16 v[100:103], v[152:155], v[192:195], v[100:103]
	v_mfma_f32_16x16x32_bf16 v[96:99], v[160:163], v[192:195], v[96:99]
	v_mfma_f32_16x16x32_bf16 v[84:87], v[152:155], v[226:229], v[84:87]
	v_mfma_f32_16x16x32_bf16 v[80:83], v[160:163], v[226:229], v[80:83]
	v_mfma_f32_16x16x32_bf16 v[68:71], v[152:155], v[234:237], v[68:71]
	v_mfma_f32_16x16x32_bf16 v[64:67], v[160:163], v[234:237], v[64:67]
	s_barrier
	s_add_i32 s65, s65, s33
	v_lshl_add_u64 v[238:239], v[238:239], 0, s[24:25]
	s_mov_b32 m0, s65
	ds_read_b128 v[164:167], v219 offset:49152
	ds_read_b128 v[168:171], v219 offset:50176
	ds_read_b128 v[172:175], v219 offset:51200
	ds_read_b128 v[192:195], v219 offset:52224
	ds_read_b128 v[222:225], v219 offset:53248
	ds_read_b128 v[226:229], v219 offset:54272
	ds_read_b128 v[230:233], v219 offset:55296
	ds_read_b128 v[234:237], v219 offset:56320
	global_load_lds_dwordx4 v[238:239], off
	s_add_i32 m0, s65, 0x2000
	s_add_u32 s46, s46, 0x40080
	v_lshl_add_u64 v[238:239], v[240:241], 0, s[24:25]
	s_addc_u32 s47, s47, 0
	s_add_i32 s65, s68, s33
	global_load_lds_dwordx4 v[238:239], off
	s_mov_b32 m0, s65
	s_or_b32 s20, s20, 1
	global_load_lds_dwordx4 v178, s[46:47]
	v_lshl_add_u64 v[238:239], s[46:47], 0, v[182:183]
	s_add_i32 m0, s65, 0x2000
	s_lshl_b64 s[46:47], s[20:21], 7
	s_add_u32 s46, s49, s46
	s_addc_u32 s47, s48, s47
	global_load_lds_dwordx4 v[238:239], off
	s_mov_b32 m0, s56
	s_nop 0
	global_load_lds_dwordx4 v176, s[46:47]
	s_mov_b32 m0, s57
	s_nop 0
	global_load_lds_dwordx4 v180, s[46:47]
	s_waitcnt vmcnt(8)
	s_waitcnt lgkmcnt(0)
	s_barrier
	v_mfma_f32_16x16x32_bf16 v[60:63], v[132:135], v[164:167], v[60:63]
	v_mfma_f32_16x16x32_bf16 v[56:59], v[140:143], v[164:167], v[56:59]
	v_mfma_f32_16x16x32_bf16 v[44:47], v[132:135], v[172:175], v[44:47]
	v_mfma_f32_16x16x32_bf16 v[40:43], v[140:143], v[172:175], v[40:43]
	v_mfma_f32_16x16x32_bf16 v[28:31], v[132:135], v[222:225], v[28:31]
	v_mfma_f32_16x16x32_bf16 v[24:27], v[140:143], v[222:225], v[24:27]
	v_mfma_f32_16x16x32_bf16 v[12:15], v[132:135], v[230:233], v[12:15]
	v_mfma_f32_16x16x32_bf16 v[8:11], v[140:143], v[230:233], v[8:11]
	v_mfma_f32_16x16x32_bf16 v[60:63], v[136:139], v[168:171], v[60:63]
	v_mfma_f32_16x16x32_bf16 v[56:59], v[144:147], v[168:171], v[56:59]
	v_mfma_f32_16x16x32_bf16 v[44:47], v[136:139], v[192:195], v[44:47]
	v_mfma_f32_16x16x32_bf16 v[40:43], v[144:147], v[192:195], v[40:43]
	v_mfma_f32_16x16x32_bf16 v[28:31], v[136:139], v[226:229], v[28:31]
	v_mfma_f32_16x16x32_bf16 v[24:27], v[144:147], v[226:229], v[24:27]
	v_mfma_f32_16x16x32_bf16 v[12:15], v[136:139], v[234:237], v[12:15]
	v_mfma_f32_16x16x32_bf16 v[8:11], v[144:147], v[234:237], v[8:11]
	v_mfma_f32_16x16x32_bf16 v[52:55], v[148:151], v[164:167], v[52:55]
	v_mfma_f32_16x16x32_bf16 v[48:51], v[156:159], v[164:167], v[48:51]
	v_mfma_f32_16x16x32_bf16 v[36:39], v[148:151], v[172:175], v[36:39]
	v_mfma_f32_16x16x32_bf16 v[32:35], v[156:159], v[172:175], v[32:35]
	v_mfma_f32_16x16x32_bf16 v[20:23], v[148:151], v[222:225], v[20:23]
	v_mfma_f32_16x16x32_bf16 v[16:19], v[156:159], v[222:225], v[16:19]
	v_mfma_f32_16x16x32_bf16 v[4:7], v[148:151], v[230:233], v[4:7]
	v_mfma_f32_16x16x32_bf16 v[0:3], v[156:159], v[230:233], v[0:3]
	v_mfma_f32_16x16x32_bf16 v[52:55], v[152:155], v[168:171], v[52:55]
	v_mfma_f32_16x16x32_bf16 v[48:51], v[160:163], v[168:171], v[48:51]
	v_mfma_f32_16x16x32_bf16 v[36:39], v[152:155], v[192:195], v[36:39]
	v_mfma_f32_16x16x32_bf16 v[32:35], v[160:163], v[192:195], v[32:35]
	v_mfma_f32_16x16x32_bf16 v[20:23], v[152:155], v[226:229], v[20:23]
	v_mfma_f32_16x16x32_bf16 v[16:19], v[160:163], v[226:229], v[16:19]
	v_mfma_f32_16x16x32_bf16 v[4:7], v[152:155], v[234:237], v[4:7]
	v_mfma_f32_16x16x32_bf16 v[0:3], v[160:163], v[234:237], v[0:3]
	s_barrier
	s_add_u32 s44, s44, 0x100
	s_addc_u32 s45, s45, 0
	s_cmp_gt_u32 s63, 13
	s_mov_b32 s63, s64
	s_cbranch_scc0 .LBB0_504
	s_and_b64 vcc, exec, s[26:27]
	s_cbranch_vccz .LBB0_507
	s_barrier

.LBB0_599:
	s_add_u32 s16, s57, s38
	ds_read_b128 v[178:181], v173
	ds_read_b128 v[182:185], v173 offset:1024
	ds_read_b128 v[186:189], v173 offset:2048
	ds_read_b128 v[190:193], v173 offset:3072
	ds_read_b128 v[194:197], v174
	ds_read_b128 v[198:201], v174 offset:1024
	ds_read_b128 v[202:205], v174 offset:2048
	ds_read_b128 v[206:209], v174 offset:3072
	s_addc_u32 s42, s58, s39
	s_cmpk_eq_i32 s38, 0x700
	s_cselect_b64 s[40:41], -1, 0
	s_and_b64 s[40:41], s[40:41], exec
	s_cselect_b32 s41, s25, s42
	s_cselect_b32 s40, s27, s16
	s_add_i32 s60, s59, 2
	s_cmpk_eq_i32 s38, 0x700
	s_cselect_b64 s[42:43], -1, 0
	s_and_b64 s[62:63], s[42:43], exec
	s_cselect_b32 s16, 0, s60
	s_and_b64 s[42:43], s[42:43], s[4:5]
	s_and_b64 s[42:43], s[42:43], exec
	s_cselect_b32 s42, s29, s37
	s_cselect_b32 s43, s28, s36
	v_lshl_add_u64 v[214:215], v[144:145], 0, s[38:39]
	s_add_i32 m0, s35, 0xc000
	ds_read_b128 v[210:213], v175
	ds_read_b128 v[218:221], v175 offset:1024
	ds_read_b128 v[222:225], v175 offset:2048
	ds_read_b128 v[226:229], v175 offset:3072
	ds_read_b128 v[230:233], v175 offset:4096
	ds_read_b128 v[234:237], v175 offset:5120
	ds_read_b128 v[238:241], v175 offset:6144
	ds_read_b128 v[242:245], v175 offset:7168
	global_load_lds_dwordx4 v[214:215], off
	v_lshl_add_u64 v[214:215], v[146:147], 0, s[38:39]
	s_add_i32 m0, s35, 0xe000
	s_nop 0
	global_load_lds_dwordx4 v[214:215], off
	s_waitcnt vmcnt(8)
	s_waitcnt lgkmcnt(0)
	s_barrier
	v_mfma_f32_16x16x32_bf16 v[124:127], v[178:181], v[210:213], v[124:127]
	v_mfma_f32_16x16x32_bf16 v[120:123], v[186:189], v[210:213], v[120:123]
	v_mfma_f32_16x16x32_bf16 v[116:119], v[178:181], v[222:225], v[116:119]
	v_mfma_f32_16x16x32_bf16 v[108:111], v[186:189], v[222:225], v[108:111]
	v_mfma_f32_16x16x32_bf16 v[100:103], v[178:181], v[230:233], v[100:103]
	v_mfma_f32_16x16x32_bf16 v[92:95], v[186:189], v[230:233], v[92:95]
	v_mfma_f32_16x16x32_bf16 v[84:87], v[178:181], v[238:241], v[84:87]
	v_mfma_f32_16x16x32_bf16 v[76:79], v[186:189], v[238:241], v[76:79]
	v_mfma_f32_16x16x32_bf16 v[124:127], v[182:185], v[218:221], v[124:127]
	v_mfma_f32_16x16x32_bf16 v[120:123], v[190:193], v[218:221], v[120:123]
	v_mfma_f32_16x16x32_bf16 v[116:119], v[182:185], v[226:229], v[116:119]
	v_mfma_f32_16x16x32_bf16 v[108:111], v[190:193], v[226:229], v[108:111]
	v_mfma_f32_16x16x32_bf16 v[100:103], v[182:185], v[234:237], v[100:103]
	v_mfma_f32_16x16x32_bf16 v[92:95], v[190:193], v[234:237], v[92:95]
	v_mfma_f32_16x16x32_bf16 v[84:87], v[182:185], v[242:245], v[84:87]
	v_mfma_f32_16x16x32_bf16 v[76:79], v[190:193], v[242:245], v[76:79]
	v_mfma_f32_16x16x32_bf16 v[112:115], v[194:197], v[210:213], v[112:115]
	v_mfma_f32_16x16x32_bf16 v[104:107], v[202:205], v[210:213], v[104:107]
	v_mfma_f32_16x16x32_bf16 v[96:99], v[194:197], v[222:225], v[96:99]
	v_mfma_f32_16x16x32_bf16 v[88:91], v[202:205], v[222:225], v[88:91]
	v_mfma_f32_16x16x32_bf16 v[80:83], v[194:197], v[230:233], v[80:83]
	v_mfma_f32_16x16x32_bf16 v[72:75], v[202:205], v[230:233], v[72:75]
	v_mfma_f32_16x16x32_bf16 v[68:71], v[194:197], v[238:241], v[68:71]
	v_mfma_f32_16x16x32_bf16 v[64:67], v[202:205], v[238:241], v[64:67]
	v_mfma_f32_16x16x32_bf16 v[112:115], v[198:201], v[218:221], v[112:115]
	v_mfma_f32_16x16x32_bf16 v[104:107], v[206:209], v[218:221], v[104:107]
	v_mfma_f32_16x16x32_bf16 v[96:99], v[198:201], v[226:229], v[96:99]
	v_mfma_f32_16x16x32_bf16 v[88:91], v[206:209], v[226:229], v[88:91]
	v_mfma_f32_16x16x32_bf16 v[80:83], v[198:201], v[234:237], v[80:83]
	v_mfma_f32_16x16x32_bf16 v[72:75], v[206:209], v[234:237], v[72:75]
	v_mfma_f32_16x16x32_bf16 v[68:71], v[198:201], v[242:245], v[68:71]
	v_mfma_f32_16x16x32_bf16 v[64:67], v[206:209], v[242:245], v[64:67]
	s_barrier
	s_add_i32 s61, s51, s33
	v_lshl_add_u64 v[214:215], s[40:41], 0, v[130:131]
	s_mov_b32 m0, s61
	ds_read_b128 v[210:213], v175 offset:16384
	ds_read_b128 v[218:221], v175 offset:17408
	ds_read_b128 v[222:225], v175 offset:18432
	ds_read_b128 v[226:229], v175 offset:19456
	ds_read_b128 v[230:233], v175 offset:20480
	ds_read_b128 v[234:237], v175 offset:21504
	ds_read_b128 v[238:241], v175 offset:22528
	ds_read_b128 v[242:245], v175 offset:23552
	global_load_lds_dwordx4 v[214:215], off
	s_add_i32 m0, s61, 0x2000
	s_add_u32 s62, s40, 0x40000
	v_lshl_add_u64 v[246:247], s[40:41], 0, v[134:135]
	s_addc_u32 s63, s41, 0
	s_add_i32 s61, s52, s33
	global_load_lds_dwordx4 v[246:247], off
	v_lshl_add_u64 v[248:249], s[62:63], 0, v[130:131]
	s_mov_b32 m0, s61
	s_nop 0
	global_load_lds_dwordx4 v[248:249], off
	v_lshl_add_u64 v[248:249], s[62:63], 0, v[134:135]
	s_add_i32 m0, s61, 0x2000
	s_lshl_b64 s[62:63], s[16:17], 7
	s_add_u32 s62, s43, s62
	s_addc_u32 s63, s42, s63
	global_load_lds_dwordx4 v[248:249], off
	v_lshl_add_u64 v[248:249], s[62:63], 0, v[128:129]
	s_mov_b32 m0, s35
	s_nop 0
	global_load_lds_dwordx4 v[248:249], off
	v_lshl_add_u64 v[248:249], s[62:63], 0, v[132:133]
	s_mov_b32 m0, s45
	s_nop 0
	global_load_lds_dwordx4 v[248:249], off
	s_waitcnt vmcnt(8)
	s_waitcnt lgkmcnt(0)
	s_barrier
	v_mfma_f32_16x16x32_bf16 v[60:63], v[178:181], v[210:213], v[60:63]
	v_mfma_f32_16x16x32_bf16 v[56:59], v[186:189], v[210:213], v[56:59]
	v_mfma_f32_16x16x32_bf16 v[52:55], v[178:181], v[222:225], v[52:55]
	v_mfma_f32_16x16x32_bf16 v[44:47], v[186:189], v[222:225], v[44:47]
	v_mfma_f32_16x16x32_bf16 v[36:39], v[178:181], v[230:233], v[36:39]
	v_mfma_f32_16x16x32_bf16 v[28:31], v[186:189], v[230:233], v[28:31]
	v_mfma_f32_16x16x32_bf16 v[16:19], v[178:181], v[238:241], v[16:19]
	v_mfma_f32_16x16x32_bf16 v[8:11], v[186:189], v[238:241], v[8:11]
	v_mfma_f32_16x16x32_bf16 v[60:63], v[182:185], v[218:221], v[60:63]
	v_mfma_f32_16x16x32_bf16 v[56:59], v[190:193], v[218:221], v[56:59]
	v_mfma_f32_16x16x32_bf16 v[52:55], v[182:185], v[226:229], v[52:55]
	v_mfma_f32_16x16x32_bf16 v[44:47], v[190:193], v[226:229], v[44:47]
	v_mfma_f32_16x16x32_bf16 v[36:39], v[182:185], v[234:237], v[36:39]
	v_mfma_f32_16x16x32_bf16 v[28:31], v[190:193], v[234:237], v[28:31]
	v_mfma_f32_16x16x32_bf16 v[16:19], v[182:185], v[242:245], v[16:19]
	v_mfma_f32_16x16x32_bf16 v[8:11], v[190:193], v[242:245], v[8:11]
	v_mfma_f32_16x16x32_bf16 v[48:51], v[194:197], v[210:213], v[48:51]
	v_mfma_f32_16x16x32_bf16 v[40:43], v[202:205], v[210:213], v[40:43]
	v_mfma_f32_16x16x32_bf16 v[32:35], v[194:197], v[222:225], v[32:35]
	v_mfma_f32_16x16x32_bf16 v[24:27], v[202:205], v[222:225], v[24:27]
	v_mfma_f32_16x16x32_bf16 v[20:23], v[194:197], v[230:233], v[20:23]
	v_mfma_f32_16x16x32_bf16 v[12:15], v[202:205], v[230:233], v[12:15]
	v_mfma_f32_16x16x32_bf16 v[4:7], v[194:197], v[238:241], v[4:7]
	v_mfma_f32_16x16x32_bf16 v[0:3], v[202:205], v[238:241], v[0:3]
	v_mfma_f32_16x16x32_bf16 v[48:51], v[198:201], v[218:221], v[48:51]
	v_mfma_f32_16x16x32_bf16 v[40:43], v[206:209], v[218:221], v[40:43]
	v_mfma_f32_16x16x32_bf16 v[32:35], v[198:201], v[226:229], v[32:35]
	v_mfma_f32_16x16x32_bf16 v[24:27], v[206:209], v[226:229], v[24:27]
	v_mfma_f32_16x16x32_bf16 v[20:23], v[198:201], v[234:237], v[20:23]
	v_mfma_f32_16x16x32_bf16 v[12:15], v[206:209], v[234:237], v[12:15]
	v_mfma_f32_16x16x32_bf16 v[4:7], v[198:201], v[242:245], v[4:7]
	v_mfma_f32_16x16x32_bf16 v[0:3], v[206:209], v[242:245], v[0:3]
	s_barrier
	s_add_i32 s61, 0, 0x18000
	v_add_u32_e32 v148, s61, v151
	s_add_i32 s64, 0, 0x1c000
	ds_read_b128 v[178:181], v148
	ds_read_b128 v[182:185], v148 offset:1024
	ds_read_b128 v[186:189], v148 offset:2048
	ds_read_b128 v[190:193], v148 offset:3072
	v_add_u32_e32 v148, s64, v151
	ds_read_b128 v[194:197], v148
	ds_read_b128 v[198:201], v148 offset:1024
	ds_read_b128 v[202:205], v148 offset:2048
	ds_read_b128 v[206:209], v148 offset:3072
	s_add_u32 s62, s62, 0x40000
	s_addc_u32 s63, s63, 0
	s_mov_b32 m0, s46
	v_lshl_add_u64 v[248:249], s[62:63], 0, v[128:129]
	ds_read_b128 v[210:213], v175 offset:32768
	ds_read_b128 v[218:221], v175 offset:33792
	ds_read_b128 v[222:225], v175 offset:34816
	ds_read_b128 v[226:229], v175 offset:35840
	ds_read_b128 v[230:233], v175 offset:36864
	ds_read_b128 v[234:237], v175 offset:37888
	ds_read_b128 v[238:241], v175 offset:38912
	ds_read_b128 v[242:245], v175 offset:39936
	global_load_lds_dwordx4 v[248:249], off
	v_lshl_add_u64 v[248:249], s[62:63], 0, v[132:133]
	s_mov_b32 m0, s47
	s_nop 0
	global_load_lds_dwordx4 v[248:249], off
	s_waitcnt vmcnt(8)
	s_waitcnt lgkmcnt(0)
	s_barrier
	v_mfma_f32_16x16x32_bf16 v[124:127], v[178:181], v[210:213], v[124:127]
	v_mfma_f32_16x16x32_bf16 v[120:123], v[186:189], v[210:213], v[120:123]
	v_mfma_f32_16x16x32_bf16 v[116:119], v[178:181], v[222:225], v[116:119]
	v_mfma_f32_16x16x32_bf16 v[108:111], v[186:189], v[222:225], v[108:111]
	v_mfma_f32_16x16x32_bf16 v[100:103], v[178:181], v[230:233], v[100:103]
	v_mfma_f32_16x16x32_bf16 v[92:95], v[186:189], v[230:233], v[92:95]
	v_mfma_f32_16x16x32_bf16 v[84:87], v[178:181], v[238:241], v[84:87]
	v_mfma_f32_16x16x32_bf16 v[76:79], v[186:189], v[238:241], v[76:79]
	v_mfma_f32_16x16x32_bf16 v[124:127], v[182:185], v[218:221], v[124:127]
	v_mfma_f32_16x16x32_bf16 v[120:123], v[190:193], v[218:221], v[120:123]
	v_mfma_f32_16x16x32_bf16 v[116:119], v[182:185], v[226:229], v[116:119]
	v_mfma_f32_16x16x32_bf16 v[108:111], v[190:193], v[226:229], v[108:111]
	v_mfma_f32_16x16x32_bf16 v[100:103], v[182:185], v[234:237], v[100:103]
	v_mfma_f32_16x16x32_bf16 v[92:95], v[190:193], v[234:237], v[92:95]
	v_mfma_f32_16x16x32_bf16 v[84:87], v[182:185], v[242:245], v[84:87]
	v_mfma_f32_16x16x32_bf16 v[76:79], v[190:193], v[242:245], v[76:79]
	v_mfma_f32_16x16x32_bf16 v[112:115], v[194:197], v[210:213], v[112:115]
	v_mfma_f32_16x16x32_bf16 v[104:107], v[202:205], v[210:213], v[104:107]
	v_mfma_f32_16x16x32_bf16 v[96:99], v[194:197], v[222:225], v[96:99]
	v_mfma_f32_16x16x32_bf16 v[88:91], v[202:205], v[222:225], v[88:91]
	v_mfma_f32_16x16x32_bf16 v[80:83], v[194:197], v[230:233], v[80:83]
	v_mfma_f32_16x16x32_bf16 v[72:75], v[202:205], v[230:233], v[72:75]
	v_mfma_f32_16x16x32_bf16 v[68:71], v[194:197], v[238:241], v[68:71]
	v_mfma_f32_16x16x32_bf16 v[64:67], v[202:205], v[238:241], v[64:67]
	v_mfma_f32_16x16x32_bf16 v[112:115], v[198:201], v[218:221], v[112:115]
	v_mfma_f32_16x16x32_bf16 v[104:107], v[206:209], v[218:221], v[104:107]
	v_mfma_f32_16x16x32_bf16 v[96:99], v[198:201], v[226:229], v[96:99]
	v_mfma_f32_16x16x32_bf16 v[88:91], v[206:209], v[226:229], v[88:91]
	v_mfma_f32_16x16x32_bf16 v[80:83], v[198:201], v[234:237], v[80:83]
	v_mfma_f32_16x16x32_bf16 v[72:75], v[206:209], v[234:237], v[72:75]
	v_mfma_f32_16x16x32_bf16 v[68:71], v[198:201], v[242:245], v[68:71]
	v_mfma_f32_16x16x32_bf16 v[64:67], v[206:209], v[242:245], v[64:67]
	s_barrier
	s_add_i32 s61, s61, s33
	v_lshl_add_u64 v[214:215], v[214:215], 0, s[20:21]
	s_mov_b32 m0, s61
	ds_read_b128 v[210:213], v175 offset:49152
	ds_read_b128 v[218:221], v175 offset:50176
	ds_read_b128 v[222:225], v175 offset:51200
	ds_read_b128 v[226:229], v175 offset:52224
	ds_read_b128 v[230:233], v175 offset:53248
	ds_read_b128 v[234:237], v175 offset:54272
	ds_read_b128 v[238:241], v175 offset:55296
	ds_read_b128 v[242:245], v175 offset:56320
	global_load_lds_dwordx4 v[214:215], off
	s_add_i32 m0, s61, 0x2000
	s_add_u32 s40, s40, 0x40080
	v_lshl_add_u64 v[214:215], v[246:247], 0, s[20:21]
	s_addc_u32 s41, s41, 0
	s_add_i32 s61, s64, s33
	global_load_lds_dwordx4 v[214:215], off
	v_lshl_add_u64 v[214:215], s[40:41], 0, v[130:131]
	s_mov_b32 m0, s61
	s_or_b32 s16, s16, 1
	global_load_lds_dwordx4 v[214:215], off
	v_lshl_add_u64 v[214:215], s[40:41], 0, v[134:135]
	s_add_i32 m0, s61, 0x2000
	s_lshl_b64 s[40:41], s[16:17], 7
	s_add_u32 s40, s43, s40
	s_addc_u32 s41, s42, s41
	global_load_lds_dwordx4 v[214:215], off
	v_lshl_add_u64 v[214:215], s[40:41], 0, v[128:129]
	s_mov_b32 m0, s49
	s_nop 0
	global_load_lds_dwordx4 v[214:215], off
	v_lshl_add_u64 v[214:215], s[40:41], 0, v[132:133]
	s_mov_b32 m0, s50
	s_nop 0
	global_load_lds_dwordx4 v[214:215], off
	s_waitcnt vmcnt(8)
	s_waitcnt lgkmcnt(0)
	s_barrier
	v_mfma_f32_16x16x32_bf16 v[60:63], v[178:181], v[210:213], v[60:63]
	v_mfma_f32_16x16x32_bf16 v[56:59], v[186:189], v[210:213], v[56:59]
	v_mfma_f32_16x16x32_bf16 v[52:55], v[178:181], v[222:225], v[52:55]
	v_mfma_f32_16x16x32_bf16 v[44:47], v[186:189], v[222:225], v[44:47]
	v_mfma_f32_16x16x32_bf16 v[36:39], v[178:181], v[230:233], v[36:39]
	v_mfma_f32_16x16x32_bf16 v[28:31], v[186:189], v[230:233], v[28:31]
	v_mfma_f32_16x16x32_bf16 v[16:19], v[178:181], v[238:241], v[16:19]
	v_mfma_f32_16x16x32_bf16 v[8:11], v[186:189], v[238:241], v[8:11]
	v_mfma_f32_16x16x32_bf16 v[60:63], v[182:185], v[218:221], v[60:63]
	v_mfma_f32_16x16x32_bf16 v[56:59], v[190:193], v[218:221], v[56:59]
	v_mfma_f32_16x16x32_bf16 v[52:55], v[182:185], v[226:229], v[52:55]
	v_mfma_f32_16x16x32_bf16 v[44:47], v[190:193], v[226:229], v[44:47]
	v_mfma_f32_16x16x32_bf16 v[36:39], v[182:185], v[234:237], v[36:39]
	v_mfma_f32_16x16x32_bf16 v[28:31], v[190:193], v[234:237], v[28:31]
	v_mfma_f32_16x16x32_bf16 v[16:19], v[182:185], v[242:245], v[16:19]
	v_mfma_f32_16x16x32_bf16 v[8:11], v[190:193], v[242:245], v[8:11]
	v_mfma_f32_16x16x32_bf16 v[48:51], v[194:197], v[210:213], v[48:51]
	v_mfma_f32_16x16x32_bf16 v[40:43], v[202:205], v[210:213], v[40:43]
	v_mfma_f32_16x16x32_bf16 v[32:35], v[194:197], v[222:225], v[32:35]
	v_mfma_f32_16x16x32_bf16 v[24:27], v[202:205], v[222:225], v[24:27]
	v_mfma_f32_16x16x32_bf16 v[20:23], v[194:197], v[230:233], v[20:23]
	v_mfma_f32_16x16x32_bf16 v[12:15], v[202:205], v[230:233], v[12:15]
	v_mfma_f32_16x16x32_bf16 v[4:7], v[194:197], v[238:241], v[4:7]
	v_mfma_f32_16x16x32_bf16 v[0:3], v[202:205], v[238:241], v[0:3]
	v_mfma_f32_16x16x32_bf16 v[48:51], v[198:201], v[218:221], v[48:51]
	v_mfma_f32_16x16x32_bf16 v[40:43], v[206:209], v[218:221], v[40:43]
	v_mfma_f32_16x16x32_bf16 v[32:35], v[198:201], v[226:229], v[32:35]
	v_mfma_f32_16x16x32_bf16 v[24:27], v[206:209], v[226:229], v[24:27]
	v_mfma_f32_16x16x32_bf16 v[20:23], v[198:201], v[234:237], v[20:23]
	v_mfma_f32_16x16x32_bf16 v[12:15], v[206:209], v[234:237], v[12:15]
	v_mfma_f32_16x16x32_bf16 v[4:7], v[198:201], v[242:245], v[4:7]
	v_mfma_f32_16x16x32_bf16 v[0:3], v[206:209], v[242:245], v[0:3]
	s_barrier
	s_add_u32 s38, s38, 0x100
	s_addc_u32 s39, s39, 0
	s_cmp_gt_u32 s59, 13
	s_mov_b32 s59, s60
	s_cbranch_scc0 .LBB0_599
	s_and_b64 vcc, exec, s[22:23]
	s_cbranch_vccz .LBB0_602
	s_barrier

.LBB0_678:
	ds_read_b128 v[144:147], v193
	ds_read_b128 v[148:151], v193 offset:1024
	ds_read_b128 v[152:155], v193 offset:2048
	ds_read_b128 v[156:159], v193 offset:3072
	ds_read_b128 v[160:163], v194
	ds_read_b128 v[164:167], v194 offset:1024
	ds_read_b128 v[168:171], v194 offset:2048
	ds_read_b128 v[172:175], v194 offset:3072
	s_cmp_eq_u32 s22, 0x7e04000
	s_cselect_b64 s[24:25], -1, 0
	s_and_b64 s[24:25], s[24:25], exec
	s_cselect_b32 s25, s9, s43
	s_cselect_b32 s24, s11, s42
	s_add_i32 s45, s44, 2
	s_cmp_eq_u32 s22, 0x7e04000
	s_cselect_b64 s[26:27], -1, 0
	s_and_b64 s[46:47], s[26:27], exec
	s_cselect_b32 s6, 0, s45
	s_and_b64 s[26:27], s[26:27], s[4:5]
	s_and_b64 s[26:27], s[26:27], exec
	s_cselect_b32 s26, s15, s21
	s_cselect_b32 s27, s14, s20
	v_lshl_add_u64 v[188:189], v[140:141], 0, s[22:23]
	s_add_i32 m0, s19, 0xc000
	ds_read_b128 v[176:179], v195
	ds_read_b128 v[180:183], v195 offset:1024
	ds_read_b128 v[184:187], v195 offset:2048
	ds_read_b128 v[196:199], v195 offset:3072
	ds_read_b128 v[200:203], v195 offset:4096
	ds_read_b128 v[204:207], v195 offset:5120
	ds_read_b128 v[208:211], v195 offset:6144
	ds_read_b128 v[212:215], v195 offset:7168
	global_load_lds_dwordx4 v[188:189], off
	v_lshl_add_u64 v[188:189], v[142:143], 0, s[22:23]
	s_add_i32 m0, s19, 0xe000
	s_nop 0
	global_load_lds_dwordx4 v[188:189], off
	s_waitcnt vmcnt(8)
	s_waitcnt lgkmcnt(0)
	s_barrier
	v_mfma_f32_16x16x32_bf16 v[124:127], v[144:147], v[176:179], v[124:127]
	v_mfma_f32_16x16x32_bf16 v[120:123], v[152:155], v[176:179], v[120:123]
	v_mfma_f32_16x16x32_bf16 v[112:115], v[144:147], v[184:187], v[112:115]
	v_mfma_f32_16x16x32_bf16 v[104:107], v[152:155], v[184:187], v[104:107]
	v_mfma_f32_16x16x32_bf16 v[96:99], v[144:147], v[200:203], v[96:99]
	v_mfma_f32_16x16x32_bf16 v[88:91], v[152:155], v[200:203], v[88:91]
	v_mfma_f32_16x16x32_bf16 v[80:83], v[144:147], v[208:211], v[80:83]
	v_mfma_f32_16x16x32_bf16 v[72:75], v[152:155], v[208:211], v[72:75]
	v_mfma_f32_16x16x32_bf16 v[124:127], v[148:151], v[180:183], v[124:127]
	v_mfma_f32_16x16x32_bf16 v[120:123], v[156:159], v[180:183], v[120:123]
	v_mfma_f32_16x16x32_bf16 v[112:115], v[148:151], v[196:199], v[112:115]
	v_mfma_f32_16x16x32_bf16 v[104:107], v[156:159], v[196:199], v[104:107]
	v_mfma_f32_16x16x32_bf16 v[96:99], v[148:151], v[204:207], v[96:99]
	v_mfma_f32_16x16x32_bf16 v[88:91], v[156:159], v[204:207], v[88:91]
	v_mfma_f32_16x16x32_bf16 v[80:83], v[148:151], v[212:215], v[80:83]
	v_mfma_f32_16x16x32_bf16 v[72:75], v[156:159], v[212:215], v[72:75]
	v_mfma_f32_16x16x32_bf16 v[116:119], v[160:163], v[176:179], v[116:119]
	v_mfma_f32_16x16x32_bf16 v[108:111], v[168:171], v[176:179], v[108:111]
	v_mfma_f32_16x16x32_bf16 v[100:103], v[160:163], v[184:187], v[100:103]
	v_mfma_f32_16x16x32_bf16 v[92:95], v[168:171], v[184:187], v[92:95]
	v_mfma_f32_16x16x32_bf16 v[84:87], v[160:163], v[200:203], v[84:87]
	v_mfma_f32_16x16x32_bf16 v[76:79], v[168:171], v[200:203], v[76:79]
	v_mfma_f32_16x16x32_bf16 v[68:71], v[160:163], v[208:211], v[68:71]
	v_mfma_f32_16x16x32_bf16 v[64:67], v[168:171], v[208:211], v[64:67]
	v_mfma_f32_16x16x32_bf16 v[116:119], v[164:167], v[180:183], v[116:119]
	v_mfma_f32_16x16x32_bf16 v[108:111], v[172:175], v[180:183], v[108:111]
	v_mfma_f32_16x16x32_bf16 v[100:103], v[164:167], v[196:199], v[100:103]
	v_mfma_f32_16x16x32_bf16 v[92:95], v[172:175], v[196:199], v[92:95]
	v_mfma_f32_16x16x32_bf16 v[84:87], v[164:167], v[204:207], v[84:87]
	v_mfma_f32_16x16x32_bf16 v[76:79], v[172:175], v[204:207], v[76:79]
	v_mfma_f32_16x16x32_bf16 v[68:71], v[164:167], v[212:215], v[68:71]
	v_mfma_f32_16x16x32_bf16 v[64:67], v[172:175], v[212:215], v[64:67]
	s_barrier
	s_add_i32 s46, s38, s29
	v_lshl_add_u64 v[188:189], s[24:25], 0, v[128:129]
	s_mov_b32 m0, s46
	ds_read_b128 v[176:179], v195 offset:16384
	ds_read_b128 v[180:183], v195 offset:17408
	ds_read_b128 v[184:187], v195 offset:18432
	ds_read_b128 v[196:199], v195 offset:19456
	ds_read_b128 v[200:203], v195 offset:20480
	ds_read_b128 v[204:207], v195 offset:21504
	ds_read_b128 v[208:211], v195 offset:22528
	ds_read_b128 v[212:215], v195 offset:23552
	global_load_lds_dwordx4 v[188:189], off
	s_add_i32 m0, s46, 0x2000
	s_add_u32 s46, s24, 0x4000
	s_addc_u32 s47, s25, 0
	s_add_i32 s48, s39, s29
	global_load_lds_dwordx4 v130, s[24:25]
	s_mov_b32 m0, s48
	s_nop 0
	global_load_lds_dwordx4 v128, s[46:47]
	v_lshl_add_u64 v[188:189], s[46:47], 0, v[130:131]
	s_add_i32 m0, s48, 0x2000
	s_lshl_b64 s[46:47], s[6:7], 21
	s_add_u32 s46, s27, s46
	s_addc_u32 s47, s26, s47
	global_load_lds_dwordx4 v[188:189], off
	s_mov_b32 m0, s19
	s_nop 0
	global_load_lds_dwordx4 v128, s[46:47]
	s_mov_b32 m0, s31
	s_nop 0
	global_load_lds_dwordx4 v130, s[46:47]
	s_waitcnt vmcnt(8)
	s_waitcnt lgkmcnt(0)
	s_barrier
	v_mfma_f32_16x16x32_bf16 v[60:63], v[144:147], v[176:179], v[60:63]
	v_mfma_f32_16x16x32_bf16 v[56:59], v[152:155], v[176:179], v[56:59]
	v_mfma_f32_16x16x32_bf16 v[48:51], v[144:147], v[184:187], v[48:51]
	v_mfma_f32_16x16x32_bf16 v[40:43], v[152:155], v[184:187], v[40:43]
	v_mfma_f32_16x16x32_bf16 v[32:35], v[144:147], v[200:203], v[32:35]
	v_mfma_f32_16x16x32_bf16 v[24:27], v[152:155], v[200:203], v[24:27]
	v_mfma_f32_16x16x32_bf16 v[16:19], v[144:147], v[208:211], v[16:19]
	v_mfma_f32_16x16x32_bf16 v[8:11], v[152:155], v[208:211], v[8:11]
	v_mfma_f32_16x16x32_bf16 v[60:63], v[148:151], v[180:183], v[60:63]
	v_mfma_f32_16x16x32_bf16 v[56:59], v[156:159], v[180:183], v[56:59]
	v_mfma_f32_16x16x32_bf16 v[48:51], v[148:151], v[196:199], v[48:51]
	v_mfma_f32_16x16x32_bf16 v[40:43], v[156:159], v[196:199], v[40:43]
	v_mfma_f32_16x16x32_bf16 v[32:35], v[148:151], v[204:207], v[32:35]
	v_mfma_f32_16x16x32_bf16 v[24:27], v[156:159], v[204:207], v[24:27]
	v_mfma_f32_16x16x32_bf16 v[16:19], v[148:151], v[212:215], v[16:19]
	v_mfma_f32_16x16x32_bf16 v[8:11], v[156:159], v[212:215], v[8:11]
	v_mfma_f32_16x16x32_bf16 v[52:55], v[160:163], v[176:179], v[52:55]
	v_mfma_f32_16x16x32_bf16 v[44:47], v[168:171], v[176:179], v[44:47]
	v_mfma_f32_16x16x32_bf16 v[36:39], v[160:163], v[184:187], v[36:39]
	v_mfma_f32_16x16x32_bf16 v[28:31], v[168:171], v[184:187], v[28:31]
	v_mfma_f32_16x16x32_bf16 v[20:23], v[160:163], v[200:203], v[20:23]
	v_mfma_f32_16x16x32_bf16 v[12:15], v[168:171], v[200:203], v[12:15]
	v_mfma_f32_16x16x32_bf16 v[4:7], v[160:163], v[208:211], v[4:7]
	v_mfma_f32_16x16x32_bf16 v[0:3], v[168:171], v[208:211], v[0:3]
	v_mfma_f32_16x16x32_bf16 v[52:55], v[164:167], v[180:183], v[52:55]
	v_mfma_f32_16x16x32_bf16 v[44:47], v[172:175], v[180:183], v[44:47]
	v_mfma_f32_16x16x32_bf16 v[36:39], v[164:167], v[196:199], v[36:39]
	v_mfma_f32_16x16x32_bf16 v[28:31], v[172:175], v[196:199], v[28:31]
	v_mfma_f32_16x16x32_bf16 v[20:23], v[164:167], v[204:207], v[20:23]
	v_mfma_f32_16x16x32_bf16 v[12:15], v[172:175], v[204:207], v[12:15]
	v_mfma_f32_16x16x32_bf16 v[4:7], v[164:167], v[212:215], v[4:7]
	v_mfma_f32_16x16x32_bf16 v[0:3], v[172:175], v[212:215], v[0:3]
	s_barrier
	s_add_i32 s48, 0, 0x18000
	s_add_i32 s49, 0, 0x1c000
	v_add_u32_e32 v156, s48, v191
	v_add_u32_e32 v172, s49, v191
	ds_read_b128 v[144:147], v156
	ds_read_b128 v[148:151], v156 offset:1024
	ds_read_b128 v[152:155], v156 offset:2048
	ds_read_b128 v[156:159], v156 offset:3072
	ds_read_b128 v[160:163], v172
	ds_read_b128 v[164:167], v172 offset:1024
	ds_read_b128 v[168:171], v172 offset:2048
	ds_read_b128 v[172:175], v172 offset:3072
	s_add_u32 s46, s46, 0x4000
	s_addc_u32 s47, s47, 0
	s_mov_b32 m0, s33
	ds_read_b128 v[176:179], v195 offset:32768
	ds_read_b128 v[180:183], v195 offset:33792
	ds_read_b128 v[184:187], v195 offset:34816
	ds_read_b128 v[196:199], v195 offset:35840
	ds_read_b128 v[200:203], v195 offset:36864
	ds_read_b128 v[204:207], v195 offset:37888
	ds_read_b128 v[208:211], v195 offset:38912
	ds_read_b128 v[212:215], v195 offset:39936
	global_load_lds_dwordx4 v128, s[46:47]
	s_mov_b32 m0, s34
	s_nop 0
	global_load_lds_dwordx4 v130, s[46:47]
	s_waitcnt vmcnt(8)
	s_waitcnt lgkmcnt(0)
	s_barrier
	v_mfma_f32_16x16x32_bf16 v[124:127], v[144:147], v[176:179], v[124:127]
	v_mfma_f32_16x16x32_bf16 v[120:123], v[152:155], v[176:179], v[120:123]
	v_mfma_f32_16x16x32_bf16 v[112:115], v[144:147], v[184:187], v[112:115]
	v_mfma_f32_16x16x32_bf16 v[104:107], v[152:155], v[184:187], v[104:107]
	v_mfma_f32_16x16x32_bf16 v[96:99], v[144:147], v[200:203], v[96:99]
	v_mfma_f32_16x16x32_bf16 v[88:91], v[152:155], v[200:203], v[88:91]
	v_mfma_f32_16x16x32_bf16 v[80:83], v[144:147], v[208:211], v[80:83]
	v_mfma_f32_16x16x32_bf16 v[72:75], v[152:155], v[208:211], v[72:75]
	v_mfma_f32_16x16x32_bf16 v[124:127], v[148:151], v[180:183], v[124:127]
	v_mfma_f32_16x16x32_bf16 v[120:123], v[156:159], v[180:183], v[120:123]
	v_mfma_f32_16x16x32_bf16 v[112:115], v[148:151], v[196:199], v[112:115]
	v_mfma_f32_16x16x32_bf16 v[104:107], v[156:159], v[196:199], v[104:107]
	v_mfma_f32_16x16x32_bf16 v[96:99], v[148:151], v[204:207], v[96:99]
	v_mfma_f32_16x16x32_bf16 v[88:91], v[156:159], v[204:207], v[88:91]
	v_mfma_f32_16x16x32_bf16 v[80:83], v[148:151], v[212:215], v[80:83]
	v_mfma_f32_16x16x32_bf16 v[72:75], v[156:159], v[212:215], v[72:75]
	v_mfma_f32_16x16x32_bf16 v[116:119], v[160:163], v[176:179], v[116:119]
	v_mfma_f32_16x16x32_bf16 v[108:111], v[168:171], v[176:179], v[108:111]
	v_mfma_f32_16x16x32_bf16 v[100:103], v[160:163], v[184:187], v[100:103]
	v_mfma_f32_16x16x32_bf16 v[92:95], v[168:171], v[184:187], v[92:95]
	v_mfma_f32_16x16x32_bf16 v[84:87], v[160:163], v[200:203], v[84:87]
	v_mfma_f32_16x16x32_bf16 v[76:79], v[168:171], v[200:203], v[76:79]
	v_mfma_f32_16x16x32_bf16 v[68:71], v[160:163], v[208:211], v[68:71]
	v_mfma_f32_16x16x32_bf16 v[64:67], v[168:171], v[208:211], v[64:67]
	v_mfma_f32_16x16x32_bf16 v[116:119], v[164:167], v[180:183], v[116:119]
	v_mfma_f32_16x16x32_bf16 v[108:111], v[172:175], v[180:183], v[108:111]
	v_mfma_f32_16x16x32_bf16 v[100:103], v[164:167], v[196:199], v[100:103]
	v_mfma_f32_16x16x32_bf16 v[92:95], v[172:175], v[196:199], v[92:95]
	v_mfma_f32_16x16x32_bf16 v[84:87], v[164:167], v[204:207], v[84:87]
	v_mfma_f32_16x16x32_bf16 v[76:79], v[172:175], v[204:207], v[76:79]
	v_mfma_f32_16x16x32_bf16 v[68:71], v[164:167], v[212:215], v[68:71]
	v_mfma_f32_16x16x32_bf16 v[64:67], v[172:175], v[212:215], v[64:67]
	s_barrier
	s_add_u32 s46, s24, 0x20000
	s_addc_u32 s47, s25, 0
	s_add_i32 s48, s48, s29
	v_lshl_add_u64 v[188:189], s[46:47], 0, v[128:129]
	s_mov_b32 m0, s48
	ds_read_b128 v[176:179], v195 offset:49152
	ds_read_b128 v[180:183], v195 offset:50176
	ds_read_b128 v[184:187], v195 offset:51200
	ds_read_b128 v[196:199], v195 offset:52224
	ds_read_b128 v[200:203], v195 offset:53248
	ds_read_b128 v[204:207], v195 offset:54272
	ds_read_b128 v[208:211], v195 offset:55296
	ds_read_b128 v[212:215], v195 offset:56320
	global_load_lds_dwordx4 v[188:189], off
	s_add_i32 m0, s48, 0x2000
	s_add_u32 s24, s24, 0x24000
	v_lshl_add_u64 v[188:189], s[46:47], 0, v[130:131]
	s_addc_u32 s25, s25, 0
	s_add_i32 s46, s49, s29
	global_load_lds_dwordx4 v[188:189], off
	s_mov_b32 m0, s46
	s_or_b32 s6, s6, 1
	global_load_lds_dwordx4 v128, s[24:25]
	v_lshl_add_u64 v[188:189], s[24:25], 0, v[130:131]
	s_add_i32 m0, s46, 0x2000
	s_lshl_b64 s[24:25], s[6:7], 21
	s_add_u32 s24, s27, s24
	s_addc_u32 s25, s26, s25
	global_load_lds_dwordx4 v[188:189], off
	s_mov_b32 m0, s36
	s_nop 0
	global_load_lds_dwordx4 v128, s[24:25]
	s_mov_b32 m0, s37
	s_nop 0
	global_load_lds_dwordx4 v130, s[24:25]
	s_waitcnt vmcnt(8)
	s_waitcnt lgkmcnt(0)
	s_barrier
	v_mfma_f32_16x16x32_bf16 v[60:63], v[144:147], v[176:179], v[60:63]
	v_mfma_f32_16x16x32_bf16 v[56:59], v[152:155], v[176:179], v[56:59]
	v_mfma_f32_16x16x32_bf16 v[48:51], v[144:147], v[184:187], v[48:51]
	v_mfma_f32_16x16x32_bf16 v[40:43], v[152:155], v[184:187], v[40:43]
	v_mfma_f32_16x16x32_bf16 v[32:35], v[144:147], v[200:203], v[32:35]
	v_mfma_f32_16x16x32_bf16 v[24:27], v[152:155], v[200:203], v[24:27]
	v_mfma_f32_16x16x32_bf16 v[16:19], v[144:147], v[208:211], v[16:19]
	v_mfma_f32_16x16x32_bf16 v[8:11], v[152:155], v[208:211], v[8:11]
	v_mfma_f32_16x16x32_bf16 v[60:63], v[148:151], v[180:183], v[60:63]
	v_mfma_f32_16x16x32_bf16 v[56:59], v[156:159], v[180:183], v[56:59]
	v_mfma_f32_16x16x32_bf16 v[48:51], v[148:151], v[196:199], v[48:51]
	v_mfma_f32_16x16x32_bf16 v[40:43], v[156:159], v[196:199], v[40:43]
	v_mfma_f32_16x16x32_bf16 v[32:35], v[148:151], v[204:207], v[32:35]
	v_mfma_f32_16x16x32_bf16 v[24:27], v[156:159], v[204:207], v[24:27]
	v_mfma_f32_16x16x32_bf16 v[16:19], v[148:151], v[212:215], v[16:19]
	v_mfma_f32_16x16x32_bf16 v[8:11], v[156:159], v[212:215], v[8:11]
	v_mfma_f32_16x16x32_bf16 v[52:55], v[160:163], v[176:179], v[52:55]
	v_mfma_f32_16x16x32_bf16 v[44:47], v[168:171], v[176:179], v[44:47]
	v_mfma_f32_16x16x32_bf16 v[36:39], v[160:163], v[184:187], v[36:39]
	v_mfma_f32_16x16x32_bf16 v[28:31], v[168:171], v[184:187], v[28:31]
	v_mfma_f32_16x16x32_bf16 v[20:23], v[160:163], v[200:203], v[20:23]
	v_mfma_f32_16x16x32_bf16 v[12:15], v[168:171], v[200:203], v[12:15]
	v_mfma_f32_16x16x32_bf16 v[4:7], v[160:163], v[208:211], v[4:7]
	v_mfma_f32_16x16x32_bf16 v[0:3], v[168:171], v[208:211], v[0:3]
	v_mfma_f32_16x16x32_bf16 v[52:55], v[164:167], v[180:183], v[52:55]
	v_mfma_f32_16x16x32_bf16 v[44:47], v[172:175], v[180:183], v[44:47]
	v_mfma_f32_16x16x32_bf16 v[36:39], v[164:167], v[196:199], v[36:39]
	v_mfma_f32_16x16x32_bf16 v[28:31], v[172:175], v[196:199], v[28:31]
	v_mfma_f32_16x16x32_bf16 v[20:23], v[164:167], v[204:207], v[20:23]
	v_mfma_f32_16x16x32_bf16 v[12:15], v[172:175], v[204:207], v[12:15]
	v_mfma_f32_16x16x32_bf16 v[4:7], v[164:167], v[212:215], v[4:7]
	v_mfma_f32_16x16x32_bf16 v[0:3], v[172:175], v[212:215], v[0:3]
	s_barrier
	s_add_u32 s22, s22, 0x400000
	s_addc_u32 s23, s23, 0
	s_add_u32 s42, s42, 0x40000
	s_addc_u32 s43, s43, 0
	s_cmp_gt_u32 s44, 61
	s_mov_b32 s44, s45
	s_cbranch_scc0 .LBB0_678
	v_lshl_or_b32 v142, s41, 8, v192
	v_lshl_add_u32 v144, s18, 8, v190
	v_ashrrev_i32_e32 v143, 31, v142
	v_ashrrev_i32_e32 v145, 31, v144
	v_lshl_add_u64 v[146:147], v[142:143], 1, s[12:13]
	v_lshlrev_b64 v[140:141], 11, v[144:145]
	v_lshl_add_u64 v[140:141], v[146:147], 0, v[140:141]
	global_load_dwordx2 v[196:197], v[140:141], off
	global_load_dwordx2 v[198:199], v[140:141], off offset:32
	global_load_dwordx2 v[200:201], v[140:141], off offset:256
	v_or_b32_e32 v202, 16, v144
	v_ashrrev_i32_e32 v203, 31, v202
	global_load_dwordx2 v[204:205], v[140:141], off offset:288
	v_lshlrev_b64 v[140:141], 11, v[202:203]
	v_lshl_add_u64 v[148:149], v[146:147], 0, v[140:141]
	global_load_dwordx2 v[206:207], v[148:149], off
	global_load_dwordx2 v[208:209], v[148:149], off offset:32
	global_load_dwordx2 v[210:211], v[148:149], off offset:256
	global_load_dwordx2 v[212:213], v[148:149], off offset:288
	v_or_b32_e32 v188, 32, v144
	v_or_b32_e32 v178, 48, v144
	v_add_u32_e32 v168, 0x80, v144
	v_add_u32_e32 v160, 0x90, v144
	v_add_u32_e32 v150, 0xa0, v144
	v_add_u32_e32 v140, 0xb0, v144
	v_ashrrev_i32_e32 v189, 31, v188
	v_ashrrev_i32_e32 v179, 31, v178
	v_ashrrev_i32_e32 v169, 31, v168
	v_ashrrev_i32_e32 v161, 31, v160
	v_ashrrev_i32_e32 v151, 31, v150
	v_ashrrev_i32_e32 v141, 31, v140
	v_lshlrev_b64 v[152:153], 12, v[144:145]
	v_lshlrev_b64 v[144:145], 2, v[142:143]
	v_lshlrev_b64 v[142:143], 11, v[188:189]
	v_lshlrev_b64 v[154:155], 11, v[178:179]
	v_lshlrev_b64 v[156:157], 11, v[168:169]
	v_lshlrev_b64 v[158:159], 11, v[160:161]
	v_lshlrev_b64 v[162:163], 11, v[150:151]
	v_lshlrev_b64 v[164:165], 11, v[140:141]
	v_lshl_add_u64 v[152:153], s[78:79], 0, v[152:153]
	v_lshl_add_u64 v[142:143], v[146:147], 0, v[142:143]
	v_lshl_add_u64 v[154:155], v[146:147], 0, v[154:155]
	v_lshl_add_u64 v[156:157], v[146:147], 0, v[156:157]
	v_lshl_add_u64 v[158:159], v[146:147], 0, v[158:159]
	v_lshl_add_u64 v[148:149], v[146:147], 0, v[162:163]
	v_lshl_add_u64 v[214:215], v[146:147], 0, v[164:165]
	v_lshl_add_u64 v[216:217], v[152:153], 0, v[144:145]
	global_load_dwordx2 v[218:219], v[142:143], off
	global_load_dwordx2 v[220:221], v[142:143], off offset:32
	global_load_dwordx2 v[222:223], v[142:143], off offset:256
	global_load_dwordx2 v[224:225], v[142:143], off offset:288
	global_load_dwordx2 v[226:227], v[154:155], off
	global_load_dwordx2 v[228:229], v[154:155], off offset:32
	global_load_dwordx2 v[186:187], v[154:155], off offset:256
	global_load_dwordx2 v[184:185], v[154:155], off offset:288
	global_load_dwordx2 v[182:183], v[156:157], off
	global_load_dwordx2 v[180:181], v[156:157], off offset:32
	global_load_dwordx2 v[176:177], v[156:157], off offset:256
	global_load_dwordx2 v[174:175], v[156:157], off offset:288
	global_load_dwordx2 v[172:173], v[158:159], off
	global_load_dwordx2 v[170:171], v[158:159], off offset:32
	global_load_dwordx2 v[166:167], v[158:159], off offset:256
	global_load_dwordx2 v[164:165], v[158:159], off offset:288
	global_load_dwordx2 v[162:163], v[148:149], off
	s_nop 0
	global_load_dwordx2 v[158:159], v[148:149], off offset:32
	global_load_dwordx2 v[156:157], v[148:149], off offset:256
	global_load_dwordx2 v[154:155], v[148:149], off offset:288
	global_load_dwordx2 v[152:153], v[214:215], off
	s_nop 0
	global_load_dwordx2 v[148:149], v[214:215], off offset:32
	global_load_dwordx2 v[146:147], v[214:215], off offset:256
	global_load_dwordx2 v[142:143], v[214:215], off offset:288
	s_and_b64 vcc, exec, s[0:1]
	s_mov_b32 s41, s8
	s_mov_b32 s18, s10
	s_mov_b64 s[22:23], s[16:17]
	s_mov_b64 s[20:21], s[14:15]
	s_waitcnt vmcnt(0)
	v_lshlrev_b32_e32 v214, 16, v196
	v_and_b32_e32 v215, 0xffff0000, v196
	v_lshlrev_b32_e32 v196, 16, v197
	v_and_b32_e32 v197, 0xffff0000, v197
	v_lshlrev_b32_e32 v230, 16, v198
	v_and_b32_e32 v231, 0xffff0000, v198
	v_lshlrev_b32_e32 v198, 16, v199
	v_and_b32_e32 v199, 0xffff0000, v199
	v_pk_add_f32 v[126:127], v[126:127], v[196:197]
	v_pk_add_f32 v[124:125], v[124:125], v[214:215]
	v_pk_add_f32 v[120:121], v[120:121], v[230:231]
	v_lshlrev_b32_e32 v232, 16, v200
	v_and_b32_e32 v233, 0xffff0000, v200
	v_pk_add_f32 v[122:123], v[122:123], v[198:199]
	global_store_dwordx4 v[216:217], v[124:127], off
	global_store_dwordx4 v[216:217], v[120:123], off offset:64
	v_pk_add_f32 v[116:117], v[116:117], v[232:233]
	s_nop 0
	v_lshlrev_b32_e32 v120, 16, v201
	v_and_b32_e32 v121, 0xffff0000, v201
	v_pk_add_f32 v[118:119], v[118:119], v[120:121]
	global_store_dwordx4 v[216:217], v[116:119], off offset:512
	s_nop 1
	v_lshlrev_b32_e32 v116, 16, v204
	v_and_b32_e32 v117, 0xffff0000, v204
	v_lshlrev_b32_e32 v118, 16, v205
	v_and_b32_e32 v119, 0xffff0000, v205
	v_pk_add_f32 v[110:111], v[110:111], v[118:119]
	v_pk_add_f32 v[108:109], v[108:109], v[116:117]
	global_store_dwordx4 v[216:217], v[108:111], off offset:576
	v_lshlrev_b64 v[116:117], 12, v[202:203]
	s_nop 0
	v_lshlrev_b32_e32 v108, 16, v206
	v_and_b32_e32 v109, 0xffff0000, v206
	v_lshlrev_b32_e32 v110, 16, v207
	v_and_b32_e32 v111, 0xffff0000, v207
	v_pk_add_f32 v[108:109], v[112:113], v[108:109]
	v_lshl_add_u64 v[112:113], s[78:79], 0, v[116:117]
	v_pk_add_f32 v[110:111], v[114:115], v[110:111]
	v_lshl_add_u64 v[112:113], v[112:113], 0, v[144:145]
	global_store_dwordx4 v[112:113], v[108:111], off
	s_nop 1
	v_lshlrev_b32_e32 v108, 16, v208
	v_and_b32_e32 v109, 0xffff0000, v208
	v_lshlrev_b32_e32 v110, 16, v209
	v_and_b32_e32 v111, 0xffff0000, v209
	v_pk_add_f32 v[106:107], v[106:107], v[110:111]
	v_pk_add_f32 v[104:105], v[104:105], v[108:109]
	global_store_dwordx4 v[112:113], v[104:107], off offset:64
	s_nop 1
	v_lshlrev_b32_e32 v104, 16, v210
	v_and_b32_e32 v105, 0xffff0000, v210
	v_lshlrev_b32_e32 v106, 16, v211
	v_and_b32_e32 v107, 0xffff0000, v211
	v_pk_add_f32 v[102:103], v[102:103], v[106:107]
	v_pk_add_f32 v[100:101], v[100:101], v[104:105]
	global_store_dwordx4 v[112:113], v[100:103], off offset:512
	s_nop 1
	v_lshlrev_b32_e32 v100, 16, v212
	v_and_b32_e32 v101, 0xffff0000, v212
	v_lshlrev_b32_e32 v102, 16, v213
	v_and_b32_e32 v103, 0xffff0000, v213
	v_pk_add_f32 v[94:95], v[94:95], v[102:103]
	v_pk_add_f32 v[92:93], v[92:93], v[100:101]
	global_store_dwordx4 v[112:113], v[92:95], off offset:576
	v_lshlrev_b64 v[100:101], 12, v[188:189]
	s_nop 0
	v_lshlrev_b32_e32 v92, 16, v218
	v_and_b32_e32 v93, 0xffff0000, v218
	v_lshlrev_b32_e32 v94, 16, v219
	v_and_b32_e32 v95, 0xffff0000, v219
	v_pk_add_f32 v[92:93], v[96:97], v[92:93]
	v_lshl_add_u64 v[96:97], s[78:79], 0, v[100:101]
	v_pk_add_f32 v[94:95], v[98:99], v[94:95]
	v_lshl_add_u64 v[96:97], v[96:97], 0, v[144:145]
	global_store_dwordx4 v[96:97], v[92:95], off
	s_nop 1
	v_lshlrev_b32_e32 v92, 16, v220
	v_and_b32_e32 v93, 0xffff0000, v220
	v_lshlrev_b32_e32 v94, 16, v221
	v_and_b32_e32 v95, 0xffff0000, v221
	v_pk_add_f32 v[90:91], v[90:91], v[94:95]
	v_pk_add_f32 v[88:89], v[88:89], v[92:93]
	global_store_dwordx4 v[96:97], v[88:91], off offset:64
	s_nop 1
	v_lshlrev_b32_e32 v88, 16, v222
	v_and_b32_e32 v89, 0xffff0000, v222
	v_lshlrev_b32_e32 v90, 16, v223
	v_and_b32_e32 v91, 0xffff0000, v223
	v_pk_add_f32 v[86:87], v[86:87], v[90:91]
	v_pk_add_f32 v[84:85], v[84:85], v[88:89]
	global_store_dwordx4 v[96:97], v[84:87], off offset:512
	s_nop 1
	v_lshlrev_b32_e32 v84, 16, v224
	v_and_b32_e32 v85, 0xffff0000, v224
	v_lshlrev_b32_e32 v86, 16, v225
	v_and_b32_e32 v87, 0xffff0000, v225
	v_pk_add_f32 v[78:79], v[78:79], v[86:87]
	v_pk_add_f32 v[76:77], v[76:77], v[84:85]
	global_store_dwordx4 v[96:97], v[76:79], off offset:576
	v_lshlrev_b64 v[84:85], 12, v[178:179]
	s_nop 0
	v_lshlrev_b32_e32 v76, 16, v226
	v_and_b32_e32 v77, 0xffff0000, v226
	v_lshlrev_b32_e32 v78, 16, v227
	v_and_b32_e32 v79, 0xffff0000, v227
	v_pk_add_f32 v[76:77], v[80:81], v[76:77]
	v_lshl_add_u64 v[80:81], s[78:79], 0, v[84:85]
	v_pk_add_f32 v[78:79], v[82:83], v[78:79]
	v_lshl_add_u64 v[80:81], v[80:81], 0, v[144:145]
	global_store_dwordx4 v[80:81], v[76:79], off
	s_nop 1
	v_lshlrev_b32_e32 v76, 16, v228
	v_and_b32_e32 v77, 0xffff0000, v228
	v_lshlrev_b32_e32 v78, 16, v229
	v_and_b32_e32 v79, 0xffff0000, v229
	v_pk_add_f32 v[74:75], v[74:75], v[78:79]
	v_pk_add_f32 v[72:73], v[72:73], v[76:77]
	global_store_dwordx4 v[80:81], v[72:75], off offset:64
	s_nop 1
	v_lshlrev_b32_e32 v72, 16, v186
	v_and_b32_e32 v73, 0xffff0000, v186
	v_lshlrev_b32_e32 v74, 16, v187
	v_and_b32_e32 v75, 0xffff0000, v187
	v_pk_add_f32 v[70:71], v[70:71], v[74:75]
	v_pk_add_f32 v[68:69], v[68:69], v[72:73]
	global_store_dwordx4 v[80:81], v[68:71], off offset:512
	s_nop 1
	v_lshlrev_b32_e32 v68, 16, v184
	v_and_b32_e32 v69, 0xffff0000, v184
	v_lshlrev_b32_e32 v70, 16, v185
	v_and_b32_e32 v71, 0xffff0000, v185
	v_pk_add_f32 v[66:67], v[66:67], v[70:71]
	v_pk_add_f32 v[64:65], v[64:65], v[68:69]
	global_store_dwordx4 v[80:81], v[64:67], off offset:576
	v_lshlrev_b32_e32 v68, 16, v183
	v_and_b32_e32 v69, 0xffff0000, v183
	v_lshlrev_b64 v[64:65], 12, v[168:169]
	v_lshlrev_b32_e32 v66, 16, v182
	v_and_b32_e32 v67, 0xffff0000, v182
	v_lshl_add_u64 v[64:65], s[78:79], 0, v[64:65]
	v_pk_add_f32 v[62:63], v[62:63], v[68:69]
	v_pk_add_f32 v[60:61], v[60:61], v[66:67]
	v_lshl_add_u64 v[64:65], v[64:65], 0, v[144:145]
	global_store_dwordx4 v[64:65], v[60:63], off
	s_nop 1
	v_lshlrev_b32_e32 v60, 16, v180
	v_and_b32_e32 v61, 0xffff0000, v180
	v_lshlrev_b32_e32 v62, 16, v181
	v_and_b32_e32 v63, 0xffff0000, v181
	v_pk_add_f32 v[58:59], v[58:59], v[62:63]
	v_pk_add_f32 v[56:57], v[56:57], v[60:61]
	global_store_dwordx4 v[64:65], v[56:59], off offset:64
	s_nop 1
	v_lshlrev_b32_e32 v56, 16, v176
	v_and_b32_e32 v57, 0xffff0000, v176
	v_lshlrev_b32_e32 v58, 16, v177
	v_and_b32_e32 v59, 0xffff0000, v177
	v_pk_add_f32 v[54:55], v[54:55], v[58:59]
	v_pk_add_f32 v[52:53], v[52:53], v[56:57]
	global_store_dwordx4 v[64:65], v[52:55], off offset:512
	s_nop 1
	v_lshlrev_b32_e32 v52, 16, v174
	v_and_b32_e32 v53, 0xffff0000, v174
	v_lshlrev_b32_e32 v54, 16, v175
	v_and_b32_e32 v55, 0xffff0000, v175
	v_pk_add_f32 v[46:47], v[46:47], v[54:55]
	v_pk_add_f32 v[44:45], v[44:45], v[52:53]
	global_store_dwordx4 v[64:65], v[44:47], off offset:576
	v_lshlrev_b64 v[52:53], 12, v[160:161]
	s_nop 0
	v_lshlrev_b32_e32 v44, 16, v172
	v_and_b32_e32 v45, 0xffff0000, v172
	v_lshlrev_b32_e32 v46, 16, v173
	v_and_b32_e32 v47, 0xffff0000, v173
	v_pk_add_f32 v[44:45], v[48:49], v[44:45]
	v_lshl_add_u64 v[48:49], s[78:79], 0, v[52:53]
	v_pk_add_f32 v[46:47], v[50:51], v[46:47]
	v_lshl_add_u64 v[48:49], v[48:49], 0, v[144:145]
	global_store_dwordx4 v[48:49], v[44:47], off
	s_nop 1
	v_lshlrev_b32_e32 v44, 16, v170
	v_and_b32_e32 v45, 0xffff0000, v170
	v_lshlrev_b32_e32 v46, 16, v171
	v_and_b32_e32 v47, 0xffff0000, v171
	v_pk_add_f32 v[42:43], v[42:43], v[46:47]
	v_pk_add_f32 v[40:41], v[40:41], v[44:45]
	global_store_dwordx4 v[48:49], v[40:43], off offset:64
	s_nop 1
	v_lshlrev_b32_e32 v40, 16, v166
	v_and_b32_e32 v41, 0xffff0000, v166
	v_lshlrev_b32_e32 v42, 16, v167
	v_and_b32_e32 v43, 0xffff0000, v167
	v_pk_add_f32 v[38:39], v[38:39], v[42:43]
	v_pk_add_f32 v[36:37], v[36:37], v[40:41]
	global_store_dwordx4 v[48:49], v[36:39], off offset:512
	s_nop 1
	v_lshlrev_b32_e32 v36, 16, v164
	v_and_b32_e32 v37, 0xffff0000, v164
	v_lshlrev_b32_e32 v38, 16, v165
	v_and_b32_e32 v39, 0xffff0000, v165
	v_pk_add_f32 v[30:31], v[30:31], v[38:39]
	v_pk_add_f32 v[28:29], v[28:29], v[36:37]
	global_store_dwordx4 v[48:49], v[28:31], off offset:576
	v_lshlrev_b64 v[36:37], 12, v[150:151]
	s_nop 0
	v_lshlrev_b32_e32 v28, 16, v162
	v_and_b32_e32 v29, 0xffff0000, v162
	v_lshlrev_b32_e32 v30, 16, v163
	v_and_b32_e32 v31, 0xffff0000, v163
	v_pk_add_f32 v[28:29], v[32:33], v[28:29]
	v_lshl_add_u64 v[32:33], s[78:79], 0, v[36:37]
	v_pk_add_f32 v[30:31], v[34:35], v[30:31]
	v_lshl_add_u64 v[32:33], v[32:33], 0, v[144:145]
	global_store_dwordx4 v[32:33], v[28:31], off
	s_nop 1
	v_lshlrev_b32_e32 v28, 16, v158
	v_and_b32_e32 v29, 0xffff0000, v158
	v_lshlrev_b32_e32 v30, 16, v159
	v_and_b32_e32 v31, 0xffff0000, v159
	v_pk_add_f32 v[26:27], v[26:27], v[30:31]
	v_pk_add_f32 v[24:25], v[24:25], v[28:29]
	global_store_dwordx4 v[32:33], v[24:27], off offset:64
	s_nop 1
	v_lshlrev_b32_e32 v24, 16, v156
	v_and_b32_e32 v25, 0xffff0000, v156
	v_lshlrev_b32_e32 v26, 16, v157
	v_and_b32_e32 v27, 0xffff0000, v157
	v_pk_add_f32 v[22:23], v[22:23], v[26:27]
	v_pk_add_f32 v[20:21], v[20:21], v[24:25]
	global_store_dwordx4 v[32:33], v[20:23], off offset:512
	s_nop 1
	v_lshlrev_b32_e32 v20, 16, v154
	v_and_b32_e32 v21, 0xffff0000, v154
	v_lshlrev_b32_e32 v22, 16, v155
	v_and_b32_e32 v23, 0xffff0000, v155
	v_pk_add_f32 v[14:15], v[14:15], v[22:23]
	v_pk_add_f32 v[12:13], v[12:13], v[20:21]
	global_store_dwordx4 v[32:33], v[12:15], off offset:576
	v_lshlrev_b64 v[20:21], 12, v[140:141]
	s_nop 0
	v_lshlrev_b32_e32 v12, 16, v152
	v_and_b32_e32 v13, 0xffff0000, v152
	v_lshlrev_b32_e32 v14, 16, v153
	v_and_b32_e32 v15, 0xffff0000, v153
	v_pk_add_f32 v[12:13], v[16:17], v[12:13]
	v_lshl_add_u64 v[16:17], s[78:79], 0, v[20:21]
	v_pk_add_f32 v[14:15], v[18:19], v[14:15]
	v_lshl_add_u64 v[16:17], v[16:17], 0, v[144:145]
	global_store_dwordx4 v[16:17], v[12:15], off
	s_nop 1
	v_lshlrev_b32_e32 v12, 16, v148
	v_and_b32_e32 v13, 0xffff0000, v148
	v_lshlrev_b32_e32 v14, 16, v149
	v_and_b32_e32 v15, 0xffff0000, v149
	v_pk_add_f32 v[10:11], v[10:11], v[14:15]
	v_pk_add_f32 v[8:9], v[8:9], v[12:13]
	global_store_dwordx4 v[16:17], v[8:11], off offset:64
	s_nop 1
	v_lshlrev_b32_e32 v8, 16, v146
	v_and_b32_e32 v9, 0xffff0000, v146
	v_lshlrev_b32_e32 v10, 16, v147
	v_and_b32_e32 v11, 0xffff0000, v147
	v_pk_add_f32 v[6:7], v[6:7], v[10:11]
	v_pk_add_f32 v[4:5], v[4:5], v[8:9]
	global_store_dwordx4 v[16:17], v[4:7], off offset:512
	s_nop 1
	v_lshlrev_b32_e32 v4, 16, v142
	v_and_b32_e32 v5, 0xffff0000, v142
	v_lshlrev_b32_e32 v6, 16, v143
	v_and_b32_e32 v7, 0xffff0000, v143
	v_pk_add_f32 v[2:3], v[2:3], v[6:7]
	v_pk_add_f32 v[0:1], v[0:1], v[4:5]
	global_store_dwordx4 v[16:17], v[0:3], off offset:576
	s_cbranch_vccz .LBB0_671
	s_waitcnt vmcnt(0)
	s_cmpk_gt_u32 s28, 0xff
	s_cbranch_scc1 .LBB0_682
	s_barrier
